# down GEMM third round: 4 workgroups share each leftover tile (K split 4 ways, f32 partials exchanged through workspace); those 64 workgroups skip the weight conversion of that phase
# speedup vs baseline: 1.0401x; 1.0205x over previous
; #define LAS __attribute__((address_space(3)))
; __device__ __forceinline__ PP get_params() { unsigned long long kp = (unsigned long long)__builtin_amdgcn_kernarg_segment_ptr(); asm volatile("" : "+s"(kp)); return (PP)kp; }
; __device__ __forceinline__ int opaque_tid(int wv) { asm volatile("" : "+s"(wv)); unsigned z = 0u; asm volatile("" : "+v"(z)); const int l = __builtin_amdgcn_mbcnt_hi(~0u, __builtin_amdgcn_mbcnt_lo(~0u, z)); return (wv << 6) | l; }
; __device__ __forceinline__ unsigned xb_add(unsigned* p, unsigned v) { return __hip_atomic_fetch_add(p, v, __ATOMIC_RELAXED, __HIP_MEMORY_SCOPE_AGENT); }
; __device__ __forceinline__ unsigned xb_xcc_id() { return (unsigned)__builtin_amdgcn_s_getreg((3 << 11) | 20) & 0xFu; }
; __device__ __forceinline__ void gbar_post(int wv, LAS unsigned char* lds) {
;     const int tid = opaque_tid(wv); unsigned* bar = (unsigned*)(get_params()->ws + WS_BAR);
;     if (tid == 0) { volatile LAS unsigned* st = (volatile LAS unsigned*)(lds + LDS_ST); st[0] = 0u; st[1] = 0u;
;         (void)xb_add(&bar[XB_XCNT(xb_xcc_id())], 1u); }
;     __syncthreads();
; }
; __global__ void __launch_bounds__(512, 2) fwd_megakernel(Params p_unused) {
;     extern __shared__ __attribute__((aligned(16))) unsigned char smem[];
;     LAS unsigned char* lds = (LAS unsigned char*)smem;
;     cg::grid_group grid = cg::this_grid();
;     const int wv = __builtin_amdgcn_readfirstlane((int)threadIdx.x >> 6);
;     gbar_post(wv, lds);
_Z14fwd_megakernel6Params:
	s_mov_b32 s101, 0
	v_and_b32_e32 v1, 0x3ff, v0
	s_add_u32 s12, s0, 0xa8
	v_readfirstlane_b32 s3, v1
	s_addc_u32 s13, s1, 0
	s_lshr_b32 s95, s3, 6
	s_mov_b32 s4, s95
	v_mov_b32_e32 v3, 0
	s_mov_b32 s81, s2
	s_load_dwordx2 s[48:49], s[0:1], 0xa8
	s_load_dword s2, s[0:1], 0xb0
	v_mov_b32_e32 v2, 0
	v_mbcnt_lo_u32_b32 v3, -1, v3
	v_mbcnt_hi_u32_b32 v3, -1, v3
	v_lshl_or_b32 v3, s4, 6, v3
	s_mov_b64 s[6:7], s[0:1]
	v_cmp_eq_u32_e32 vcc, 0, v3
	s_and_saveexec_b64 s[4:5], vcc
	s_cbranch_execz .LBB0_3
	s_add_i32 s10, 0, 0x253f0
	v_mov_b32_e32 v3, s10
	s_add_i32 s10, 0, 0x253f4
	s_mov_b64 s[8:9], exec
	ds_write_b32 v3, v2
	v_mov_b32_e32 v3, s10
	ds_write_b32 v3, v2
	v_mbcnt_lo_u32_b32 v3, s8, 0
	v_mbcnt_hi_u32_b32 v3, s9, v3
	v_cmp_eq_u32_e32 vcc, 0, v3
	s_getreg_b32 s10, hwreg(HW_REG_XCC_ID, 0, 4)
	s_and_b64 s[14:15], exec, vcc
	s_mov_b64 exec, s[14:15]
	s_cbranch_execz .LBB0_3
	s_load_dwordx2 s[6:7], s[6:7], 0xa0
	s_lshl_b32 s10, s10, 8
	s_and_b32 s10, s10, 0xf00
	v_mov_b32_e32 v3, 0x285da000
	s_waitcnt lgkmcnt(0)
	s_add_u32 s6, s6, s10
	s_addc_u32 s7, s7, 0
	s_bcnt1_i32_b64 s8, s[8:9]
	v_mov_b32_e32 v4, s8
	global_atomic_add v3, v4, s[6:7] offset:3072

; #define LAS __attribute__((address_space(3)))
; __device__ __forceinline__ int opaque_bid() { int t = blockIdx.x; asm volatile("" : "+s"(t)); return t; }
;     __device__ bool next(int i, Unit& u) const {
;         const long L = (long)i * G + c; if (L >= nwg) return false;
;         int wgid = (int)L; { const int q = nwg / NXCD, r = nwg % NXCD, xcd = wgid % NXCD, off = wgid / NXCD; wgid = (xcd < r ? xcd * (q + 1) : r * (q + 1) + (xcd - r) * q) + off; }
;         const int nig = WGM * nN, gid = wgid / nig, fm = gid * WGM, gsz = (nM - fm) < WGM ? (nM - fm) : WGM;
;         u.pm = fm + ((wgid % nig) % gsz); u.pn = (wgid % nig) / gsz; return true;
;     }
; template <int LDA, int LDB, int M, int N, int K, class Epi>
; __device__ __forceinline__ void run_gemm(int wv, LAS unsigned char* lds, const bf16_t* A, const bf16_t* Bt, const Epi& E) {
;     pg8::Gemm g; g.A = A; g.Bt = Bt;
;     pg8::StaticOrder S; S.init(M, N, (int)gridDim.x, opaque_bid());
;     pg8::gemm_phase<Epi, LDA, LDB, K>(wv, lds, g, S, E);
.LBB0_911:
	s_or_b64 exec, exec, s[4:5]
	s_mov_b32 s100, 0
	s_mov_b32 s101, 0
	s_mov_b64 s[4:5], s[0:1]
	s_waitcnt lgkmcnt(0)
	s_barrier
	s_load_dwordx4 s[12:15], s[4:5], 0x98
	s_mov_b32 s26, s81
	s_mov_b32 s4, s95
	v_mov_b32_e32 v0, v3
	s_cmpk_lt_i32 s26, 0x210
	v_mbcnt_lo_u32_b32 v0, -1, v0
	v_mbcnt_hi_u32_b32 v20, -1, v0
	v_lshl_or_b32 v0, s4, 6, v20
	s_cselect_b64 s[4:5], -1, 0
	s_cmpk_gt_i32 s26, 0x20f
	v_readfirstlane_b32 s27, v0
	s_cbranch_scc1 .LBB0_913
	s_ashr_i32 s6, s26, 31
	s_lshr_b32 s6, s6, 29
	s_add_i32 s6, s26, s6
	s_ashr_i32 s7, s6, 3
	s_and_b32 s6, s6, -8
	s_sub_i32 s6, s26, s6
	s_cmp_lt_i32 s6, 0
	s_movk_i32 s8, 0x43
	s_cselect_b32 s8, s8, 0x42
	s_mul_i32 s6, s8, s6
	s_add_i32 s6, s6, s7
	s_ashr_i32 s7, s6, 31
	s_lshr_b32 s7, s7, 26
	s_add_i32 s7, s6, s7
	s_ashr_i32 s8, s7, 6
	s_lshl_b32 s8, s8, 3
	s_sub_i32 s9, 0x42, s8
	s_min_u32 s9, s9, 8
	s_andn2_b32 s7, s7, 63
	s_sub_i32 s10, s6, s7
	v_cvt_f32_ubyte0_e32 v2, s9
	v_cvt_f32_i32_e32 v1, s10
	v_rcp_iflag_f32_e32 v4, v2
	s_ashr_i32 s6, s10, 30
	s_or_b32 s11, s6, 1
	v_mul_f32_e32 v4, v1, v4
	v_trunc_f32_e32 v4, v4
	v_fma_f32 v1, -v4, v2, v1
	v_cvt_i32_f32_e32 v4, v4
	v_cmp_ge_f32_e64 s[6:7], |v1|, v2
	s_and_b64 s[6:7], s[6:7], exec
	s_cselect_b32 s6, s11, 0
	v_readfirstlane_b32 s7, v4
	s_add_i32 s6, s7, s6
	s_sext_i32_i8 s45, s6
	s_mul_i32 s6, s6, s9
	s_sub_i32 s6, s10, s6
	s_sext_i32_i8 s6, s6
	s_add_i32 s46, s8, s6

;     __device__ bool next(int i, Unit& u) const {
;         const long L = (long)i * G + c; if (L >= nwg) return false;
;         int wgid = (int)L; { const int q = nwg / NXCD, r = nwg % NXCD, xcd = wgid % NXCD, off = wgid / NXCD; wgid = (xcd < r ? xcd * (q + 1) : r * (q + 1) + (xcd - r) * q) + off; }
;         const int nig = WGM * nN, gid = wgid / nig, fm = gid * WGM, gsz = (nM - fm) < WGM ? (nM - fm) : WGM;
;         u.pm = fm + ((wgid % nig) % gsz); u.pn = (wgid % nig) / gsz; return true;
;     }
; template <class Epi, int LDA, int LDB, int KK>
; __device__ __forceinline__ void gemm_phase(int wv, LAS unsigned char* lds, const Gemm g, const StaticOrder& S, const Epi& E) {
;     ...
;         const bool has_next = S.next(ui + 1, nxt);
;         const char* nA = has_next ? (const char*)g.A + (size_t)nxt.pm * tstepA : cA; const char* nB = has_next ? (const char*)g.Bt + (size_t)nxt.pn * tstepB : cB;
.LBB0_917:
	s_or_b64 exec, exec, s[18:19]
	s_mov_b32 s100, s101
	s_and_b64 vcc, exec, s[6:7]
	s_mov_b32 s45, s43
	s_mov_b32 s46, s44
	s_mov_b64 s[20:21], s[10:11]
	s_mov_b64 s[18:19], s[8:9]
	s_cbranch_vccnz .LBB0_942
.LBB0_918:
	s_add_i32 s41, s41, 1
	s_mul_i32 s6, s41, s49
	s_mul_hi_u32 s7, s41, s48
	s_add_i32 s7, s7, s6
	s_mul_i32 s6, s41, s48
	s_add_u32 s10, s6, s26
	s_addc_u32 s11, s7, s42
	s_mov_b32 s101, 0
	s_cmp_lt_u32 s10, 0x200
	s_cbranch_scc1 .Ldn_h1
	s_sub_u32 s98, s10, 0x200
	s_lshr_b32 s99, s98, 4
	s_and_b32 s98, s98, 15
	s_add_u32 s10, s98, 0x200
	s_add_u32 s101, s99, 1
	s_cmp_lt_u32 s99, 4
	s_cbranch_scc1 .Ldn_h1
	s_movk_i32 s10, 0x210
	s_mov_b32 s101, 0
.Ldn_h1:
	v_cmp_gt_i64_e64 s[6:7], s[10:11], v[198:199]
	v_cmp_lt_i64_e64 s[8:9], s[10:11], v[200:201]
	s_and_b64 vcc, exec, s[6:7]
	s_cbranch_vccnz .LBB0_920
	s_ashr_i32 s11, s10, 31
	s_lshr_b32 s11, s11, 29
	s_add_i32 s11, s10, s11
	s_ashr_i32 s22, s11, 3
	s_and_b32 s11, s11, -8
	s_sub_i32 s10, s10, s11
	s_cmp_lt_i32 s10, 0
	s_movk_i32 s11, 0x43
	s_cselect_b32 s11, s11, 0x42
	s_mul_i32 s10, s11, s10
	s_add_i32 s10, s10, s22
	s_ashr_i32 s11, s10, 31
	s_lshr_b32 s11, s11, 26
	s_add_i32 s11, s10, s11
	s_ashr_i32 s22, s11, 6
	s_lshl_b32 s22, s22, 3
	s_sub_i32 s23, 0x42, s22
	s_min_i32 s23, s23, 8
	s_abs_i32 s24, s23
	v_cvt_f32_u32_e32 v4, s24
	s_sub_i32 s43, 0, s24
	s_andn2_b32 s11, s11, 63
	s_sub_i32 s10, s10, s11
	v_rcp_iflag_f32_e32 v4, v4
	s_abs_i32 s11, s10
	s_xor_b32 s25, s10, s23
	s_ashr_i32 s25, s25, 31
	v_mul_f32_e32 v4, 0x4f7ffffe, v4
	v_cvt_u32_f32_e32 v4, v4
	s_nop 0
	v_readfirstlane_b32 s44, v4
	s_mul_i32 s43, s43, s44
	s_mul_hi_u32 s43, s44, s43
	s_add_i32 s44, s44, s43
	s_mul_hi_u32 s43, s11, s44
	s_mul_i32 s44, s43, s24
	s_sub_i32 s11, s11, s44
	s_add_i32 s47, s43, 1
	s_sub_i32 s44, s11, s24
	s_cmp_ge_u32 s11, s24
	s_cselect_b32 s43, s47, s43
	s_cselect_b32 s11, s44, s11
	s_add_i32 s44, s43, 1
	s_cmp_ge_u32 s11, s24
	s_cselect_b32 s11, s44, s43
	s_xor_b32 s11, s11, s25
	s_sub_i32 s43, s11, s25
	s_mul_i32 s11, s43, s23
	s_sub_i32 s10, s10, s11
	s_add_i32 s44, s10, s22

; #define PG8_STAGE(bufoff, gbase, voff) do { _Pragma("unroll") for (int _i = 0; _i < 2; ++_i) \
;         __builtin_amdgcn_global_load_lds((const unsigned*)((const char*)(gbase) + (voff)[_i]), (LAS unsigned*)(lds + (bufoff) + ldsw + _i * 8192), 16, 0, 0); } while (0)
; #define PG8_LDA(dst, b, h) do { _Pragma("unroll") for (int m = 0; m < 4; ++m) _Pragma("unroll") for (int k = 0; k < 2; ++k) dst[m][k] = *(const LAS bf16x8*)(lds + PG8_SA(b, h) + aoff + m * 2048 + k * 1024); } while (0)
; #define PG8_LDB(dst, b, h) do { _Pragma("unroll") for (int n = 0; n < 2; ++n) _Pragma("unroll") for (int k = 0; k < 2; ++k) dst[n][k] = *(const LAS bf16x8*)(lds + PG8_SB(b, h) + boff + n * 2048 + k * 1024); } while (0)
; #define PG8_MMA(ai, bj, At, Bt) do { __builtin_amdgcn_s_setprio(1); _Pragma("unroll") for (int m = 0; m < 4; ++m) _Pragma("unroll") for (int n = 0; n < 2; ++n) _Pragma("unroll") for (int k = 0; k < 2; ++k) \
;         acc[ai][bj][m][n] = __builtin_amdgcn_mfma_f32_16x16x32_bf16(Bt[n][k], At[m][k], acc[ai][bj][m][n], 0, 0, 0); __builtin_amdgcn_s_setprio(0); } while (0)
; #define PG8_WAIT_L(n) asm volatile("s_waitcnt lgkmcnt(" #n ")" ::: "memory")
; #define PG8_BAR __builtin_amdgcn_s_barrier()
; #define PG8_SCHED __builtin_amdgcn_sched_barrier(0)
; template <class Epi, int LDA, int LDB, int KK>
; __device__ __forceinline__ void gemm_phase(int wv, LAS unsigned char* lds, const Gemm g, const StaticOrder& S, const Epi& E) {
;     ...
;           for (; t < tend; t += 2) {
;             const bool last = (t == nt - 2);
;             const char* a1 = cA + (size_t)(t + 1) * kstep;
;             const char* a2 = last ? nA : cA + (size_t)(t + 2) * kstep; const char* b2 = last ? nB : cB + (size_t)(t + 2) * kstep;
;             const char* a3 = a2 + kstep; const char* b3 = b2 + kstep;
;             PG8_LDB(B0, 0, 0); PG8_SCHED; PG8_LDA(At, 0, 0); PG8_STAGE(PG8_SA(1, 1), a1 + hstepA, voffA);
;             PG8_WAIT_L(8); PG8_BAR; PG8_WAIT_L(0); PG8_MMA(0, 0, At, B0); PG8_BAR; PG8_SCHED;
;     ...
; #pragma unroll
;         for (int a = 0; a < 2; ++a)
; #pragma unroll
;             for (int b = 0; b < 2; ++b)
; #pragma unroll
;                 for (int m = 0; m < 4; ++m)
; #pragma unroll
;                     for (int n = 0; n < 2; ++n) acc[a][b][m][n] = (f32x4){0.f, 0.f, 0.f, 0.f};
.LBB0_924:
	s_cmp_eq_u32 s101, 0
	s_cbranch_scc1 .Ldn_h2
	s_sub_u32 s98, s101, 1
	s_mul_i32 s98, s98, 0xb00
	s_add_u32 s8, s8, s98
	s_addc_u32 s9, s9, 0
	s_add_u32 s10, s10, s98
	s_addc_u32 s11, s11, 0
.Ldn_h2:
	s_add_u32 s47, s20, 0x100
	v_mov_b32_e32 v4, 0
	s_addc_u32 s55, s21, 0
	s_mov_b32 s56, -2
	s_cmp_eq_u32 s100, 0
	s_cselect_b32 s56, s56, 64
	s_waitcnt lgkmcnt(0)
	v_mov_b32_e32 v5, v4
	v_mov_b32_e32 v6, v4
	v_mov_b32_e32 v7, v4
	v_mov_b32_e32 v8, v4
	v_mov_b32_e32 v9, v4
	v_mov_b32_e32 v10, v4
	v_mov_b32_e32 v11, v4
	v_mov_b32_e32 v20, v4
	v_mov_b32_e32 v21, v4
	v_mov_b32_e32 v22, v4
	v_mov_b32_e32 v23, v4
	v_mov_b32_e32 v24, v4
	v_mov_b32_e32 v25, v4
	v_mov_b32_e32 v26, v4
	v_mov_b32_e32 v27, v4
	v_mov_b32_e32 v36, v4
	v_mov_b32_e32 v37, v4
	v_mov_b32_e32 v38, v4
	v_mov_b32_e32 v39, v4
	v_mov_b32_e32 v40, v4
	v_mov_b32_e32 v41, v4
	v_mov_b32_e32 v42, v4
	v_mov_b32_e32 v43, v4
	v_mov_b32_e32 v52, v4
	v_mov_b32_e32 v53, v4
	v_mov_b32_e32 v54, v4
	v_mov_b32_e32 v55, v4
	v_mov_b32_e32 v56, v4
	v_mov_b32_e32 v57, v4
	v_mov_b32_e32 v58, v4
	v_mov_b32_e32 v59, v4
	v_mov_b32_e32 v12, v4
	v_mov_b32_e32 v13, v4
	v_mov_b32_e32 v14, v4
	v_mov_b32_e32 v15, v4
	v_mov_b32_e32 v16, v4
	v_mov_b32_e32 v17, v4
	v_mov_b32_e32 v18, v4
	v_mov_b32_e32 v19, v4
	v_mov_b32_e32 v28, v4
	v_mov_b32_e32 v29, v4
	v_mov_b32_e32 v30, v4
	v_mov_b32_e32 v31, v4
	v_mov_b32_e32 v32, v4
	v_mov_b32_e32 v33, v4
	v_mov_b32_e32 v34, v4
	v_mov_b32_e32 v35, v4
	v_mov_b32_e32 v44, v4
	v_mov_b32_e32 v45, v4
	v_mov_b32_e32 v46, v4
	v_mov_b32_e32 v47, v4
	v_mov_b32_e32 v48, v4
	v_mov_b32_e32 v49, v4
	v_mov_b32_e32 v50, v4
	v_mov_b32_e32 v51, v4
	v_mov_b32_e32 v60, v4
	v_mov_b32_e32 v61, v4
	v_mov_b32_e32 v62, v4
	v_mov_b32_e32 v63, v4
	v_mov_b32_e32 v64, v4
	v_mov_b32_e32 v65, v4
	v_mov_b32_e32 v66, v4
	v_mov_b32_e32 v67, v4
	v_mov_b32_e32 v68, v4
	v_mov_b32_e32 v69, v4
	v_mov_b32_e32 v70, v4
	v_mov_b32_e32 v71, v4
	v_mov_b32_e32 v72, v4
	v_mov_b32_e32 v73, v4
	v_mov_b32_e32 v74, v4
	v_mov_b32_e32 v75, v4
	v_mov_b32_e32 v84, v4
	v_mov_b32_e32 v85, v4
	v_mov_b32_e32 v86, v4
	v_mov_b32_e32 v87, v4
	v_mov_b32_e32 v88, v4
	v_mov_b32_e32 v89, v4
	v_mov_b32_e32 v90, v4
	v_mov_b32_e32 v91, v4
	v_mov_b32_e32 v100, v4
	v_mov_b32_e32 v101, v4
	v_mov_b32_e32 v102, v4
	v_mov_b32_e32 v103, v4
	v_mov_b32_e32 v104, v4
	v_mov_b32_e32 v105, v4
	v_mov_b32_e32 v106, v4
	v_mov_b32_e32 v107, v4
	v_mov_b32_e32 v116, v4
	v_mov_b32_e32 v117, v4
	v_mov_b32_e32 v118, v4
	v_mov_b32_e32 v119, v4
	v_mov_b32_e32 v120, v4
	v_mov_b32_e32 v121, v4
	v_mov_b32_e32 v122, v4
	v_mov_b32_e32 v123, v4
	v_mov_b32_e32 v76, v4
	v_mov_b32_e32 v77, v4
	v_mov_b32_e32 v78, v4
	v_mov_b32_e32 v79, v4
	v_mov_b32_e32 v80, v4
	v_mov_b32_e32 v81, v4
	v_mov_b32_e32 v82, v4
	v_mov_b32_e32 v83, v4
	v_mov_b32_e32 v92, v4
	v_mov_b32_e32 v93, v4
	v_mov_b32_e32 v94, v4
	v_mov_b32_e32 v95, v4
	v_mov_b32_e32 v96, v4
	v_mov_b32_e32 v97, v4
	v_mov_b32_e32 v98, v4
	v_mov_b32_e32 v99, v4
	v_mov_b32_e32 v108, v4
	v_mov_b32_e32 v109, v4
	v_mov_b32_e32 v110, v4
	v_mov_b32_e32 v111, v4
	v_mov_b32_e32 v112, v4
	v_mov_b32_e32 v113, v4
	v_mov_b32_e32 v114, v4
	v_mov_b32_e32 v115, v4
	v_mov_b32_e32 v124, v4
	v_mov_b32_e32 v125, v4
	v_mov_b32_e32 v126, v4
	v_mov_b32_e32 v127, v4
	v_mov_b32_e32 v128, v4
	v_mov_b32_e32 v129, v4
	v_mov_b32_e32 v130, v4
	v_mov_b32_e32 v131, v4
	v_add_u32_e32 v180, 0x10000, v230
	ds_read_b128 v[132:135], v180 offset:0
	ds_read_b128 v[136:139], v180 offset:2048
	ds_read_b128 v[140:143], v180 offset:16384
	ds_read_b128 v[144:147], v180 offset:18432
	ds_read_b128 v[148:151], v234 offset:0
	ds_read_b128 v[152:155], v234 offset:2048
	ds_read_b128 v[156:159], v234 offset:4096
	ds_read_b128 v[160:163], v234 offset:6144
.Ldown_loop:
	s_add_u32 s20, s18, 0x100
	s_addc_u32 s21, s19, 0
	s_cmpk_eq_i32 s56, 0x54
	s_cselect_b32 s25, s9, s21
	s_cselect_b32 s24, s8, s20
	s_cselect_b32 s23, s11, s55
	s_cselect_b32 s22, s10, s47
	s_waitcnt lgkmcnt(0)
	v_mfma_f32_16x16x32_bf16 v[128:131], v[132:135], v[148:151], v[128:131]
	ds_read_b128 v[202:205], v180 offset:1024
	v_mfma_f32_16x16x32_bf16 v[124:127], v[136:139], v[148:151], v[124:127]
	ds_read_b128 v[206:209], v180 offset:3072
	v_mfma_f32_16x16x32_bf16 v[120:123], v[140:143], v[148:151], v[120:123]
	ds_read_b128 v[210:213], v180 offset:17408
	v_mfma_f32_16x16x32_bf16 v[116:119], v[144:147], v[148:151], v[116:119]
	ds_read_b128 v[214:217], v180 offset:19456
	v_mfma_f32_16x16x32_bf16 v[112:115], v[132:135], v[152:155], v[112:115]
	ds_read_b128 v[164:167], v234 offset:1024
	v_mfma_f32_16x16x32_bf16 v[108:111], v[136:139], v[152:155], v[108:111]
	ds_read_b128 v[168:171], v234 offset:3072
	v_mfma_f32_16x16x32_bf16 v[104:107], v[140:143], v[152:155], v[104:107]
	ds_read_b128 v[172:175], v234 offset:5120
	v_mfma_f32_16x16x32_bf16 v[100:103], v[144:147], v[152:155], v[100:103]
	ds_read_b128 v[176:179], v234 offset:7168
	v_mfma_f32_16x16x32_bf16 v[96:99], v[132:135], v[156:159], v[96:99]
	v_mfma_f32_16x16x32_bf16 v[92:95], v[136:139], v[156:159], v[92:95]
	v_mfma_f32_16x16x32_bf16 v[88:91], v[140:143], v[156:159], v[88:91]
	v_mfma_f32_16x16x32_bf16 v[84:87], v[144:147], v[156:159], v[84:87]
	v_mfma_f32_16x16x32_bf16 v[80:83], v[132:135], v[160:163], v[80:83]
	v_mfma_f32_16x16x32_bf16 v[76:79], v[136:139], v[160:163], v[76:79]
	v_mfma_f32_16x16x32_bf16 v[72:75], v[140:143], v[160:163], v[72:75]
	v_mfma_f32_16x16x32_bf16 v[68:71], v[144:147], v[160:163], v[68:71]
	s_waitcnt vmcnt(8) lgkmcnt(0)
	s_barrier
; #define PG8_STAGE(bufoff, gbase, voff) do { _Pragma("unroll") for (int _i = 0; _i < 2; ++_i) \
;         __builtin_amdgcn_global_load_lds((const unsigned*)((const char*)(gbase) + (voff)[_i]), (LAS unsigned*)(lds + (bufoff) + ldsw + _i * 8192), 16, 0, 0); } while (0)
; #define PG8_LDA(dst, b, h) do { _Pragma("unroll") for (int m = 0; m < 4; ++m) _Pragma("unroll") for (int k = 0; k < 2; ++k) dst[m][k] = *(const LAS bf16x8*)(lds + PG8_SA(b, h) + aoff + m * 2048 + k * 1024); } while (0)
; #define PG8_WAIT_V(n) asm volatile("s_waitcnt vmcnt(" #n ")" ::: "memory")
; #define PG8_BAR __builtin_amdgcn_s_barrier()
; template <class Epi, int LDA, int LDB, int KK>
; __device__ __forceinline__ void gemm_phase(int wv, LAS unsigned char* lds, const Gemm g, const StaticOrder& S, const Epi& E) {
;     ...
;           for (; t < tend; t += 2) {
;             const bool last = (t == nt - 2);
;             const char* a1 = cA + (size_t)(t + 1) * kstep;
;             const char* a2 = last ? nA : cA + (size_t)(t + 2) * kstep; const char* b2 = last ? nB : cB + (size_t)(t + 2) * kstep;
;             const char* a3 = a2 + kstep; const char* b3 = b2 + kstep;
;             PG8_LDB(B0, 0, 0); PG8_SCHED; PG8_LDA(At, 0, 0); PG8_STAGE(PG8_SA(1, 1), a1 + hstepA, voffA);
;             PG8_WAIT_L(8); PG8_BAR; PG8_WAIT_L(0); PG8_MMA(0, 0, At, B0); PG8_BAR; PG8_SCHED;
;             PG8_LDB(B1, 0, 1); PG8_STAGE(PG8_SB(0, 0), b2, voffB);
;             PG8_BAR; PG8_WAIT_L(0); PG8_MMA(0, 1, At, B1); PG8_BAR;
;             PG8_LDA(At, 0, 1); PG8_STAGE(PG8_SA(0, 0), a2, voffA);
;             PG8_BAR; PG8_WAIT_L(0); PG8_MMA(1, 0, At, B0); PG8_BAR; PG8_SCHED;
;             PG8_STAGE(PG8_SB(0, 1), b2 + hstepB, voffB);
;             PG8_WAIT_V(6); PG8_BAR; PG8_MMA(1, 1, At, B1); PG8_BAR;
;             PG8_LDB(B0, 1, 0); PG8_SCHED; PG8_LDA(At, 1, 0); PG8_STAGE(PG8_SA(0, 1), a2 + hstepA, voffA);
;             PG8_WAIT_L(8); PG8_BAR; PG8_WAIT_L(0); PG8_MMA(0, 0, At, B0); PG8_BAR; PG8_SCHED;
;             PG8_LDB(B1, 1, 1); PG8_STAGE(PG8_SB(1, 0), b3, voffB);
;             PG8_BAR; PG8_WAIT_L(0); PG8_MMA(0, 1, At, B1); PG8_BAR;
;             PG8_LDA(At, 1, 1); PG8_STAGE(PG8_SA(1, 0), a3, voffA);
;             PG8_BAR; PG8_WAIT_L(0); PG8_MMA(1, 0, At, B0); PG8_BAR; PG8_SCHED;
;             PG8_STAGE(PG8_SB(1, 1), b3 + hstepB, voffB);
;             PG8_WAIT_V(6); PG8_BAR; PG8_MMA(1, 1, At, B1); PG8_BAR;
	v_mfma_f32_16x16x32_bf16 v[128:131], v[202:205], v[164:167], v[128:131]
	ds_read_b128 v[148:151], v234 offset:16384
	v_mfma_f32_16x16x32_bf16 v[124:127], v[206:209], v[164:167], v[124:127]
	ds_read_b128 v[152:155], v234 offset:18432
	v_mfma_f32_16x16x32_bf16 v[120:123], v[210:213], v[164:167], v[120:123]
	ds_read_b128 v[156:159], v234 offset:20480
	v_mfma_f32_16x16x32_bf16 v[116:119], v[214:217], v[164:167], v[116:119]
	ds_read_b128 v[160:163], v234 offset:22528
	v_mfma_f32_16x16x32_bf16 v[112:115], v[202:205], v[168:171], v[112:115]
	v_lshl_add_u64 v[182:183], s[22:23], 0, v[2:3]
	s_add_i32 m0, s35, 0x10000
	v_mfma_f32_16x16x32_bf16 v[108:111], v[206:209], v[168:171], v[108:111]
	global_load_lds_dwordx4 v[182:183], off
	v_mfma_f32_16x16x32_bf16 v[104:107], v[210:213], v[168:171], v[104:107]
	v_mfma_f32_16x16x32_bf16 v[100:103], v[214:217], v[168:171], v[100:103]
	v_lshl_add_u64 v[182:183], s[22:23], 0, v[190:191]
	s_add_i32 m0, s35, 0x12000
	v_mfma_f32_16x16x32_bf16 v[96:99], v[202:205], v[172:175], v[96:99]
	global_load_lds_dwordx4 v[182:183], off
	v_mfma_f32_16x16x32_bf16 v[92:95], v[206:209], v[172:175], v[92:95]
	v_mfma_f32_16x16x32_bf16 v[88:91], v[210:213], v[172:175], v[88:91]
	v_lshl_add_u64 v[182:183], s[24:25], 0, v[0:1]
	s_mov_b32 m0, s35
	v_mfma_f32_16x16x32_bf16 v[84:87], v[214:217], v[172:175], v[84:87]
	global_load_lds_dwordx4 v[182:183], off
	v_mfma_f32_16x16x32_bf16 v[80:83], v[202:205], v[176:179], v[80:83]
	v_mfma_f32_16x16x32_bf16 v[76:79], v[206:209], v[176:179], v[76:79]
	v_mfma_f32_16x16x32_bf16 v[72:75], v[210:213], v[176:179], v[72:75]
	v_mfma_f32_16x16x32_bf16 v[68:71], v[214:217], v[176:179], v[68:71]
	s_waitcnt lgkmcnt(0)
	v_mfma_f32_16x16x32_bf16 v[64:67], v[132:135], v[148:151], v[64:67]
	ds_read_b128 v[164:167], v234 offset:17408
	v_mfma_f32_16x16x32_bf16 v[60:63], v[136:139], v[148:151], v[60:63]
	ds_read_b128 v[168:171], v234 offset:19456
	v_mfma_f32_16x16x32_bf16 v[56:59], v[140:143], v[148:151], v[56:59]
	ds_read_b128 v[172:175], v234 offset:21504
	v_mfma_f32_16x16x32_bf16 v[52:55], v[144:147], v[148:151], v[52:55]
	ds_read_b128 v[176:179], v234 offset:23552
	v_mfma_f32_16x16x32_bf16 v[48:51], v[132:135], v[152:155], v[48:51]
	v_lshl_add_u64 v[182:183], s[24:25], 0, v[188:189]
	s_add_i32 m0, s35, 0x2000
	v_mfma_f32_16x16x32_bf16 v[44:47], v[136:139], v[152:155], v[44:47]
	global_load_lds_dwordx4 v[182:183], off
	v_mfma_f32_16x16x32_bf16 v[40:43], v[140:143], v[152:155], v[40:43]
	v_mfma_f32_16x16x32_bf16 v[36:39], v[144:147], v[152:155], v[36:39]
	s_add_u32 s98, s22, 0x160000
	s_addc_u32 s99, s23, 0
	v_lshl_add_u64 v[182:183], s[98:99], 0, v[2:3]
	s_add_i32 m0, s35, 0x14000
	v_mfma_f32_16x16x32_bf16 v[32:35], v[132:135], v[156:159], v[32:35]
	global_load_lds_dwordx4 v[182:183], off
	v_mfma_f32_16x16x32_bf16 v[28:31], v[136:139], v[156:159], v[28:31]
	v_mfma_f32_16x16x32_bf16 v[24:27], v[140:143], v[156:159], v[24:27]
	v_lshl_add_u64 v[182:183], s[98:99], 0, v[190:191]
	s_add_i32 m0, s35, 0x16000
	v_mfma_f32_16x16x32_bf16 v[20:23], v[144:147], v[156:159], v[20:23]
	global_load_lds_dwordx4 v[182:183], off
	v_mfma_f32_16x16x32_bf16 v[16:19], v[132:135], v[160:163], v[16:19]
	v_mfma_f32_16x16x32_bf16 v[12:15], v[136:139], v[160:163], v[12:15]
	v_mfma_f32_16x16x32_bf16 v[8:11], v[140:143], v[160:163], v[8:11]
	v_mfma_f32_16x16x32_bf16 v[4:7], v[144:147], v[160:163], v[4:7]
	s_waitcnt vmcnt(8) lgkmcnt(0)
	s_barrier
	v_mfma_f32_16x16x32_bf16 v[64:67], v[202:205], v[164:167], v[64:67]
	ds_read_b128 v[132:135], v180 offset:32768
	v_mfma_f32_16x16x32_bf16 v[60:63], v[206:209], v[164:167], v[60:63]
	ds_read_b128 v[136:139], v180 offset:34816
	v_mfma_f32_16x16x32_bf16 v[56:59], v[210:213], v[164:167], v[56:59]
	ds_read_b128 v[140:143], v180 offset:49152
	v_mfma_f32_16x16x32_bf16 v[52:55], v[214:217], v[164:167], v[52:55]
	ds_read_b128 v[144:147], v180 offset:51200
	v_mfma_f32_16x16x32_bf16 v[48:51], v[202:205], v[168:171], v[48:51]
	ds_read_b128 v[148:151], v234 offset:32768
	v_mfma_f32_16x16x32_bf16 v[44:47], v[206:209], v[168:171], v[44:47]
	ds_read_b128 v[152:155], v234 offset:34816
	v_mfma_f32_16x16x32_bf16 v[40:43], v[210:213], v[168:171], v[40:43]
	ds_read_b128 v[156:159], v234 offset:36864
	v_mfma_f32_16x16x32_bf16 v[36:39], v[214:217], v[168:171], v[36:39]
	ds_read_b128 v[160:163], v234 offset:38912
	v_mfma_f32_16x16x32_bf16 v[32:35], v[202:205], v[172:175], v[32:35]
	s_add_u32 s98, s24, 0x2c0000
	s_addc_u32 s99, s25, 0
	v_lshl_add_u64 v[182:183], s[98:99], 0, v[0:1]
	s_add_i32 m0, s35, 0x4000
	v_mfma_f32_16x16x32_bf16 v[28:31], v[206:209], v[172:175], v[28:31]
	global_load_lds_dwordx4 v[182:183], off
	v_mfma_f32_16x16x32_bf16 v[24:27], v[210:213], v[172:175], v[24:27]
	v_mfma_f32_16x16x32_bf16 v[20:23], v[214:217], v[172:175], v[20:23]
	v_lshl_add_u64 v[182:183], s[98:99], 0, v[188:189]
	s_add_i32 m0, s35, 0x6000
	v_mfma_f32_16x16x32_bf16 v[16:19], v[202:205], v[176:179], v[16:19]
	global_load_lds_dwordx4 v[182:183], off
	v_mfma_f32_16x16x32_bf16 v[12:15], v[206:209], v[176:179], v[12:15]
	v_mfma_f32_16x16x32_bf16 v[8:11], v[210:213], v[176:179], v[8:11]
	v_mfma_f32_16x16x32_bf16 v[4:7], v[214:217], v[176:179], v[4:7]
	s_add_u32 s22, s22, 0x80
	s_addc_u32 s23, s23, 0
	s_add_u32 s24, s24, 0x80
	s_addc_u32 s25, s25, 0
	s_waitcnt lgkmcnt(0)
	v_mfma_f32_16x16x32_bf16 v[128:131], v[132:135], v[148:151], v[128:131]
	ds_read_b128 v[202:205], v180 offset:33792
	v_mfma_f32_16x16x32_bf16 v[124:127], v[136:139], v[148:151], v[124:127]
	ds_read_b128 v[206:209], v180 offset:35840
	v_mfma_f32_16x16x32_bf16 v[120:123], v[140:143], v[148:151], v[120:123]
	ds_read_b128 v[210:213], v180 offset:50176
	v_mfma_f32_16x16x32_bf16 v[116:119], v[144:147], v[148:151], v[116:119]
	ds_read_b128 v[214:217], v180 offset:52224
	v_mfma_f32_16x16x32_bf16 v[112:115], v[132:135], v[152:155], v[112:115]
	ds_read_b128 v[164:167], v234 offset:33792
	v_mfma_f32_16x16x32_bf16 v[108:111], v[136:139], v[152:155], v[108:111]
	ds_read_b128 v[168:171], v234 offset:35840
	v_mfma_f32_16x16x32_bf16 v[104:107], v[140:143], v[152:155], v[104:107]
	ds_read_b128 v[172:175], v234 offset:37888
	v_mfma_f32_16x16x32_bf16 v[100:103], v[144:147], v[152:155], v[100:103]
	ds_read_b128 v[176:179], v234 offset:39936
	v_mfma_f32_16x16x32_bf16 v[96:99], v[132:135], v[156:159], v[96:99]
	v_mfma_f32_16x16x32_bf16 v[92:95], v[136:139], v[156:159], v[92:95]
	v_mfma_f32_16x16x32_bf16 v[88:91], v[140:143], v[156:159], v[88:91]
	v_mfma_f32_16x16x32_bf16 v[84:87], v[144:147], v[156:159], v[84:87]
	v_mfma_f32_16x16x32_bf16 v[80:83], v[132:135], v[160:163], v[80:83]
	v_mfma_f32_16x16x32_bf16 v[76:79], v[136:139], v[160:163], v[76:79]
	v_mfma_f32_16x16x32_bf16 v[72:75], v[140:143], v[160:163], v[72:75]
	v_mfma_f32_16x16x32_bf16 v[68:71], v[144:147], v[160:163], v[68:71]
	s_waitcnt vmcnt(8) lgkmcnt(0)
	s_barrier
; #define PG8_STAGE(bufoff, gbase, voff) do { _Pragma("unroll") for (int _i = 0; _i < 2; ++_i) \
;         __builtin_amdgcn_global_load_lds((const unsigned*)((const char*)(gbase) + (voff)[_i]), (LAS unsigned*)(lds + (bufoff) + ldsw + _i * 8192), 16, 0, 0); } while (0)
; #define PG8_LDA(dst, b, h) do { _Pragma("unroll") for (int m = 0; m < 4; ++m) _Pragma("unroll") for (int k = 0; k < 2; ++k) dst[m][k] = *(const LAS bf16x8*)(lds + PG8_SA(b, h) + aoff + m * 2048 + k * 1024); } while (0)
; #define PG8_WAIT_V(n) asm volatile("s_waitcnt vmcnt(" #n ")" ::: "memory")
; template <class Epi, int LDA, int LDB, int KK>
; __device__ __forceinline__ void gemm_phase(int wv, LAS unsigned char* lds, const Gemm g, const StaticOrder& S, const Epi& E) {
;     ...
;           for (; t < tend; t += 2) {
;             const bool last = (t == nt - 2);
;             const char* a1 = cA + (size_t)(t + 1) * kstep;
;             const char* a2 = last ? nA : cA + (size_t)(t + 2) * kstep; const char* b2 = last ? nB : cB + (size_t)(t + 2) * kstep;
;             const char* a3 = a2 + kstep; const char* b3 = b2 + kstep;
;             PG8_LDB(B0, 0, 0); PG8_SCHED; PG8_LDA(At, 0, 0); PG8_STAGE(PG8_SA(1, 1), a1 + hstepA, voffA);
;             PG8_WAIT_L(8); PG8_BAR; PG8_WAIT_L(0); PG8_MMA(0, 0, At, B0); PG8_BAR; PG8_SCHED;
;             PG8_LDB(B1, 0, 1); PG8_STAGE(PG8_SB(0, 0), b2, voffB);
;             PG8_BAR; PG8_WAIT_L(0); PG8_MMA(0, 1, At, B1); PG8_BAR;
;             PG8_LDA(At, 0, 1); PG8_STAGE(PG8_SA(0, 0), a2, voffA);
;             PG8_BAR; PG8_WAIT_L(0); PG8_MMA(1, 0, At, B0); PG8_BAR; PG8_SCHED;
;             PG8_STAGE(PG8_SB(0, 1), b2 + hstepB, voffB);
;             PG8_WAIT_V(6); PG8_BAR; PG8_MMA(1, 1, At, B1); PG8_BAR;
;             PG8_LDB(B0, 1, 0); PG8_SCHED; PG8_LDA(At, 1, 0); PG8_STAGE(PG8_SA(0, 1), a2 + hstepA, voffA);
;             PG8_WAIT_L(8); PG8_BAR; PG8_WAIT_L(0); PG8_MMA(0, 0, At, B0); PG8_BAR; PG8_SCHED;
;             PG8_LDB(B1, 1, 1); PG8_STAGE(PG8_SB(1, 0), b3, voffB);
;             PG8_BAR; PG8_WAIT_L(0); PG8_MMA(0, 1, At, B1); PG8_BAR;
;             PG8_LDA(At, 1, 1); PG8_STAGE(PG8_SA(1, 0), a3, voffA);
;             PG8_BAR; PG8_WAIT_L(0); PG8_MMA(1, 0, At, B0); PG8_BAR; PG8_SCHED;
;             PG8_STAGE(PG8_SB(1, 1), b3 + hstepB, voffB);
;             PG8_WAIT_V(6); PG8_BAR; PG8_MMA(1, 1, At, B1); PG8_BAR;
;           }
	v_mfma_f32_16x16x32_bf16 v[128:131], v[202:205], v[164:167], v[128:131]
	ds_read_b128 v[148:151], v234 offset:49152
	v_mfma_f32_16x16x32_bf16 v[124:127], v[206:209], v[164:167], v[124:127]
	ds_read_b128 v[152:155], v234 offset:51200
	v_mfma_f32_16x16x32_bf16 v[120:123], v[210:213], v[164:167], v[120:123]
	ds_read_b128 v[156:159], v234 offset:53248
	v_mfma_f32_16x16x32_bf16 v[116:119], v[214:217], v[164:167], v[116:119]
	ds_read_b128 v[160:163], v234 offset:55296
	v_mfma_f32_16x16x32_bf16 v[112:115], v[202:205], v[168:171], v[112:115]
	v_lshl_add_u64 v[182:183], s[22:23], 0, v[2:3]
	s_add_i32 m0, s35, 0x18000
	v_mfma_f32_16x16x32_bf16 v[108:111], v[206:209], v[168:171], v[108:111]
	global_load_lds_dwordx4 v[182:183], off
	v_mfma_f32_16x16x32_bf16 v[104:107], v[210:213], v[168:171], v[104:107]
	v_mfma_f32_16x16x32_bf16 v[100:103], v[214:217], v[168:171], v[100:103]
	v_lshl_add_u64 v[182:183], s[22:23], 0, v[190:191]
	s_add_i32 m0, s35, 0x1a000
	v_mfma_f32_16x16x32_bf16 v[96:99], v[202:205], v[172:175], v[96:99]
	global_load_lds_dwordx4 v[182:183], off
	v_mfma_f32_16x16x32_bf16 v[92:95], v[206:209], v[172:175], v[92:95]
	v_mfma_f32_16x16x32_bf16 v[88:91], v[210:213], v[172:175], v[88:91]
	v_lshl_add_u64 v[182:183], s[24:25], 0, v[0:1]
	s_add_i32 m0, s35, 0x8000
	v_mfma_f32_16x16x32_bf16 v[84:87], v[214:217], v[172:175], v[84:87]
	global_load_lds_dwordx4 v[182:183], off
	v_mfma_f32_16x16x32_bf16 v[80:83], v[202:205], v[176:179], v[80:83]
	v_mfma_f32_16x16x32_bf16 v[76:79], v[206:209], v[176:179], v[76:79]
	v_mfma_f32_16x16x32_bf16 v[72:75], v[210:213], v[176:179], v[72:75]
	v_mfma_f32_16x16x32_bf16 v[68:71], v[214:217], v[176:179], v[68:71]
	s_waitcnt lgkmcnt(0)
	v_mfma_f32_16x16x32_bf16 v[64:67], v[132:135], v[148:151], v[64:67]
	ds_read_b128 v[164:167], v234 offset:50176
	v_mfma_f32_16x16x32_bf16 v[60:63], v[136:139], v[148:151], v[60:63]
	ds_read_b128 v[168:171], v234 offset:52224
	v_mfma_f32_16x16x32_bf16 v[56:59], v[140:143], v[148:151], v[56:59]
	ds_read_b128 v[172:175], v234 offset:54272
	v_mfma_f32_16x16x32_bf16 v[52:55], v[144:147], v[148:151], v[52:55]
	ds_read_b128 v[176:179], v234 offset:56320
	v_mfma_f32_16x16x32_bf16 v[48:51], v[132:135], v[152:155], v[48:51]
	v_lshl_add_u64 v[182:183], s[24:25], 0, v[188:189]
	s_add_i32 m0, s35, 0xa000
	v_mfma_f32_16x16x32_bf16 v[44:47], v[136:139], v[152:155], v[44:47]
	global_load_lds_dwordx4 v[182:183], off
	v_mfma_f32_16x16x32_bf16 v[40:43], v[140:143], v[152:155], v[40:43]
	v_mfma_f32_16x16x32_bf16 v[36:39], v[144:147], v[152:155], v[36:39]
	s_add_u32 s98, s22, 0x160000
	s_addc_u32 s99, s23, 0
	v_lshl_add_u64 v[182:183], s[98:99], 0, v[2:3]
	s_add_i32 m0, s35, 0x1c000
	v_mfma_f32_16x16x32_bf16 v[32:35], v[132:135], v[156:159], v[32:35]
	global_load_lds_dwordx4 v[182:183], off
	v_mfma_f32_16x16x32_bf16 v[28:31], v[136:139], v[156:159], v[28:31]
	v_mfma_f32_16x16x32_bf16 v[24:27], v[140:143], v[156:159], v[24:27]
	v_lshl_add_u64 v[182:183], s[98:99], 0, v[190:191]
	s_add_i32 m0, s35, 0x1e000
	v_mfma_f32_16x16x32_bf16 v[20:23], v[144:147], v[156:159], v[20:23]
	global_load_lds_dwordx4 v[182:183], off
	v_mfma_f32_16x16x32_bf16 v[16:19], v[132:135], v[160:163], v[16:19]
	v_mfma_f32_16x16x32_bf16 v[12:15], v[136:139], v[160:163], v[12:15]
	v_mfma_f32_16x16x32_bf16 v[8:11], v[140:143], v[160:163], v[8:11]
	v_mfma_f32_16x16x32_bf16 v[4:7], v[144:147], v[160:163], v[4:7]
	s_waitcnt vmcnt(8) lgkmcnt(0)
	s_barrier
	v_mfma_f32_16x16x32_bf16 v[64:67], v[202:205], v[164:167], v[64:67]
	ds_read_b128 v[132:135], v180 offset:0
	v_mfma_f32_16x16x32_bf16 v[60:63], v[206:209], v[164:167], v[60:63]
	ds_read_b128 v[136:139], v180 offset:2048
	v_mfma_f32_16x16x32_bf16 v[56:59], v[210:213], v[164:167], v[56:59]
	ds_read_b128 v[140:143], v180 offset:16384
	v_mfma_f32_16x16x32_bf16 v[52:55], v[214:217], v[164:167], v[52:55]
	ds_read_b128 v[144:147], v180 offset:18432
	v_mfma_f32_16x16x32_bf16 v[48:51], v[202:205], v[168:171], v[48:51]
	ds_read_b128 v[148:151], v234 offset:0
	v_mfma_f32_16x16x32_bf16 v[44:47], v[206:209], v[168:171], v[44:47]
	ds_read_b128 v[152:155], v234 offset:2048
	v_mfma_f32_16x16x32_bf16 v[40:43], v[210:213], v[168:171], v[40:43]
	ds_read_b128 v[156:159], v234 offset:4096
	v_mfma_f32_16x16x32_bf16 v[36:39], v[214:217], v[168:171], v[36:39]
	ds_read_b128 v[160:163], v234 offset:6144
	v_mfma_f32_16x16x32_bf16 v[32:35], v[202:205], v[172:175], v[32:35]
	s_add_u32 s98, s24, 0x2c0000
	s_addc_u32 s99, s25, 0
	v_lshl_add_u64 v[182:183], s[98:99], 0, v[0:1]
	s_add_i32 m0, s35, 0xc000
	v_mfma_f32_16x16x32_bf16 v[28:31], v[206:209], v[172:175], v[28:31]
	global_load_lds_dwordx4 v[182:183], off
	v_mfma_f32_16x16x32_bf16 v[24:27], v[210:213], v[172:175], v[24:27]
	v_mfma_f32_16x16x32_bf16 v[20:23], v[214:217], v[172:175], v[20:23]
	v_lshl_add_u64 v[182:183], s[98:99], 0, v[188:189]
	s_add_i32 m0, s35, 0xe000
	v_mfma_f32_16x16x32_bf16 v[16:19], v[202:205], v[176:179], v[16:19]
	global_load_lds_dwordx4 v[182:183], off
	v_mfma_f32_16x16x32_bf16 v[12:15], v[206:209], v[176:179], v[12:15]
	v_mfma_f32_16x16x32_bf16 v[8:11], v[210:213], v[176:179], v[8:11]
	v_mfma_f32_16x16x32_bf16 v[4:7], v[214:217], v[176:179], v[4:7]
	s_add_i32 s56, s56, 2
	s_add_u32 s47, s47, 0x100
	s_addc_u32 s55, s55, 0
	s_cmpk_gt_u32 s56, 0x55
	s_mov_b64 s[18:19], s[20:21]
	s_cbranch_scc0 .Ldown_loop
; #define LAS __attribute__((address_space(3)))
; template <class Epi, int LDA, int LDB, int KK>
; __device__ __forceinline__ void gemm_phase(int wv, LAS unsigned char* lds, const Gemm g, const StaticOrder& S, const Epi& E) {
;     ...
;         E(acc, cur, wr, wc, fr, fq, (const LAS float*)(lds + 131072 + (ui % 3) * 1024));
;         if (!has_next) break;
	s_waitcnt lgkmcnt(0)
	s_cmp_eq_u32 s100, 0
	s_cbranch_scc1 .Ldn_epi
	s_cmp_eq_u32 s100, 4
	s_cbranch_scc1 .Ldn_owner
	s_and_b32 s98, s81, 15
	s_mul_i32 s98, s98, 3
	s_add_u32 s98, s98, s100
	s_sub_u32 s98, s98, 1
	s_lshl_b32 s98, s98, 18
	s_add_u32 s98, s98, 0x1f000000
	s_add_u32 s98, s14, s98
	s_addc_u32 s99, s15, 0
	v_mbcnt_lo_u32_b32 v132, -1, 0
	v_mbcnt_hi_u32_b32 v132, -1, v132
	v_lshl_or_b32 v132, s95, 6, v132
	v_lshlrev_b32_e32 v132, 4, v132
	global_store_dwordx4 v132, v[4:7], s[98:99] sc0 sc1
	v_add_u32_e32 v132, 0x2000, v132
	global_store_dwordx4 v132, v[8:11], s[98:99] sc0 sc1
	v_add_u32_e32 v132, 0x2000, v132
	global_store_dwordx4 v132, v[12:15], s[98:99] sc0 sc1
	v_add_u32_e32 v132, 0x2000, v132
	global_store_dwordx4 v132, v[16:19], s[98:99] sc0 sc1
	v_add_u32_e32 v132, 0x2000, v132
	global_store_dwordx4 v132, v[20:23], s[98:99] sc0 sc1
	v_add_u32_e32 v132, 0x2000, v132
	global_store_dwordx4 v132, v[24:27], s[98:99] sc0 sc1
	v_add_u32_e32 v132, 0x2000, v132
	global_store_dwordx4 v132, v[28:31], s[98:99] sc0 sc1
	v_add_u32_e32 v132, 0x2000, v132
	global_store_dwordx4 v132, v[32:35], s[98:99] sc0 sc1
	v_add_u32_e32 v132, 0x2000, v132
	global_store_dwordx4 v132, v[36:39], s[98:99] sc0 sc1
	v_add_u32_e32 v132, 0x2000, v132
	global_store_dwordx4 v132, v[40:43], s[98:99] sc0 sc1
	v_add_u32_e32 v132, 0x2000, v132
	global_store_dwordx4 v132, v[44:47], s[98:99] sc0 sc1
	v_add_u32_e32 v132, 0x2000, v132
	global_store_dwordx4 v132, v[48:51], s[98:99] sc0 sc1
	v_add_u32_e32 v132, 0x2000, v132
	global_store_dwordx4 v132, v[52:55], s[98:99] sc0 sc1
	v_add_u32_e32 v132, 0x2000, v132
	global_store_dwordx4 v132, v[56:59], s[98:99] sc0 sc1
	v_add_u32_e32 v132, 0x2000, v132
	global_store_dwordx4 v132, v[60:63], s[98:99] sc0 sc1
	v_add_u32_e32 v132, 0x2000, v132
	global_store_dwordx4 v132, v[64:67], s[98:99] sc0 sc1
	v_add_u32_e32 v132, 0x2000, v132
	global_store_dwordx4 v132, v[68:71], s[98:99] sc0 sc1
	v_add_u32_e32 v132, 0x2000, v132
	global_store_dwordx4 v132, v[72:75], s[98:99] sc0 sc1
	v_add_u32_e32 v132, 0x2000, v132
	global_store_dwordx4 v132, v[76:79], s[98:99] sc0 sc1
	v_add_u32_e32 v132, 0x2000, v132
	global_store_dwordx4 v132, v[80:83], s[98:99] sc0 sc1
	v_add_u32_e32 v132, 0x2000, v132
	global_store_dwordx4 v132, v[84:87], s[98:99] sc0 sc1
	v_add_u32_e32 v132, 0x2000, v132
	global_store_dwordx4 v132, v[88:91], s[98:99] sc0 sc1
	v_add_u32_e32 v132, 0x2000, v132
	global_store_dwordx4 v132, v[92:95], s[98:99] sc0 sc1
	v_add_u32_e32 v132, 0x2000, v132
	global_store_dwordx4 v132, v[96:99], s[98:99] sc0 sc1
	v_add_u32_e32 v132, 0x2000, v132
	global_store_dwordx4 v132, v[100:103], s[98:99] sc0 sc1
	v_add_u32_e32 v132, 0x2000, v132
	global_store_dwordx4 v132, v[104:107], s[98:99] sc0 sc1
	v_add_u32_e32 v132, 0x2000, v132
	global_store_dwordx4 v132, v[108:111], s[98:99] sc0 sc1
	v_add_u32_e32 v132, 0x2000, v132
	global_store_dwordx4 v132, v[112:115], s[98:99] sc0 sc1
	v_add_u32_e32 v132, 0x2000, v132
	global_store_dwordx4 v132, v[116:119], s[98:99] sc0 sc1
	v_add_u32_e32 v132, 0x2000, v132
	global_store_dwordx4 v132, v[120:123], s[98:99] sc0 sc1
	v_add_u32_e32 v132, 0x2000, v132
	global_store_dwordx4 v132, v[124:127], s[98:99] sc0 sc1
	v_add_u32_e32 v132, 0x2000, v132
	global_store_dwordx4 v132, v[128:131], s[98:99] sc0 sc1
	s_waitcnt vmcnt(0)
	s_barrier
	s_cmp_lg_u32 s95, 0
	s_cbranch_scc1 .Ldn_p_done
	s_and_b32 s98, s81, 15
	s_lshl_b32 s98, s98, 2
	s_add_u32 s98, s98, 0x285da900
	s_add_u32 s98, s14, s98
	s_addc_u32 s99, s15, 0
	s_mov_b64 exec, 1
	v_mov_b32_e32 v132, 0
	v_mov_b32_e32 v133, 1
	global_atomic_add v132, v133, s[98:99]
	s_mov_b64 exec, -1

; #define LAS __attribute__((address_space(3)))
; template <class Epi, int LDA, int LDB, int KK>
; __device__ __forceinline__ void gemm_phase(int wv, LAS unsigned char* lds, const Gemm g, const StaticOrder& S, const Epi& E) {
;     ...
;         E(acc, cur, wr, wc, fr, fq, (const LAS float*)(lds + 131072 + (ui % 3) * 1024));
;         if (!has_next) break;
.Ldn_owner:
	s_cmp_lg_u32 s95, 0
	s_cbranch_scc1 .Ldn_o_wait
	s_and_b32 s98, s81, 15
	s_lshl_b32 s98, s98, 2
	s_add_u32 s98, s98, 0x285da900
	s_add_u32 s98, s14, s98
	s_addc_u32 s99, s15, 0
	s_add_u32 s100, s2, 1
	s_mul_i32 s100, s100, 3
	s_mov_b64 exec, 1
	v_mov_b32_e32 v132, 0
.Ldn_poll:
	s_sleep 2
	global_load_dword v133, v132, s[98:99] sc1
	s_waitcnt vmcnt(0)
	v_cmp_gt_u32_e32 vcc, s100, v133
	s_cbranch_vccnz .Ldn_poll
	buffer_inv sc1
	s_waitcnt vmcnt(0)
	s_mov_b64 exec, -1
.Ldn_o_wait:
	s_barrier
	s_and_b32 s98, s81, 15
	s_mul_i32 s98, s98, 3
	s_lshl_b32 s98, s98, 18
	s_add_u32 s98, s98, 0x1f000000
	s_add_u32 s98, s14, s98
	s_addc_u32 s99, s15, 0
	v_mbcnt_lo_u32_b32 v132, -1, 0
	v_mbcnt_hi_u32_b32 v132, -1, v132
	v_lshl_or_b32 v132, s95, 6, v132
	v_lshlrev_b32_e32 v132, 4, v132
	global_load_dwordx4 v[136:139], v132, s[98:99] sc0 sc1
	v_add_u32_e32 v132, 0x2000, v132
	global_load_dwordx4 v[140:143], v132, s[98:99] sc0 sc1
	v_add_u32_e32 v132, 0x2000, v132
	global_load_dwordx4 v[144:147], v132, s[98:99] sc0 sc1
	v_add_u32_e32 v132, 0x2000, v132
	global_load_dwordx4 v[148:151], v132, s[98:99] sc0 sc1
	v_add_u32_e32 v132, 0x2000, v132
	global_load_dwordx4 v[152:155], v132, s[98:99] sc0 sc1
	v_add_u32_e32 v132, 0x2000, v132
	global_load_dwordx4 v[156:159], v132, s[98:99] sc0 sc1
	v_add_u32_e32 v132, 0x2000, v132
	global_load_dwordx4 v[160:163], v132, s[98:99] sc0 sc1
	v_add_u32_e32 v132, 0x2000, v132
	global_load_dwordx4 v[164:167], v132, s[98:99] sc0 sc1
	v_add_u32_e32 v132, 0x2000, v132
	s_waitcnt vmcnt(7)
	v_pk_add_f32 v[4:5], v[4:5], v[136:137]
	v_pk_add_f32 v[6:7], v[6:7], v[138:139]
	s_waitcnt vmcnt(6)
	v_pk_add_f32 v[8:9], v[8:9], v[140:141]
	v_pk_add_f32 v[10:11], v[10:11], v[142:143]
	s_waitcnt vmcnt(5)
	v_pk_add_f32 v[12:13], v[12:13], v[144:145]
	v_pk_add_f32 v[14:15], v[14:15], v[146:147]
	s_waitcnt vmcnt(4)
	v_pk_add_f32 v[16:17], v[16:17], v[148:149]
	v_pk_add_f32 v[18:19], v[18:19], v[150:151]
	s_waitcnt vmcnt(3)
	v_pk_add_f32 v[20:21], v[20:21], v[152:153]
	v_pk_add_f32 v[22:23], v[22:23], v[154:155]
	s_waitcnt vmcnt(2)
	v_pk_add_f32 v[24:25], v[24:25], v[156:157]
	v_pk_add_f32 v[26:27], v[26:27], v[158:159]
	s_waitcnt vmcnt(1)
	v_pk_add_f32 v[28:29], v[28:29], v[160:161]
	v_pk_add_f32 v[30:31], v[30:31], v[162:163]
	s_waitcnt vmcnt(0)
	v_pk_add_f32 v[32:33], v[32:33], v[164:165]
	v_pk_add_f32 v[34:35], v[34:35], v[166:167]
	global_load_dwordx4 v[136:139], v132, s[98:99] sc0 sc1
	v_add_u32_e32 v132, 0x2000, v132
	global_load_dwordx4 v[140:143], v132, s[98:99] sc0 sc1
	v_add_u32_e32 v132, 0x2000, v132
	global_load_dwordx4 v[144:147], v132, s[98:99] sc0 sc1
	v_add_u32_e32 v132, 0x2000, v132
	global_load_dwordx4 v[148:151], v132, s[98:99] sc0 sc1
	v_add_u32_e32 v132, 0x2000, v132
	global_load_dwordx4 v[152:155], v132, s[98:99] sc0 sc1
	v_add_u32_e32 v132, 0x2000, v132
	global_load_dwordx4 v[156:159], v132, s[98:99] sc0 sc1
	v_add_u32_e32 v132, 0x2000, v132
	global_load_dwordx4 v[160:163], v132, s[98:99] sc0 sc1
	v_add_u32_e32 v132, 0x2000, v132
	global_load_dwordx4 v[164:167], v132, s[98:99] sc0 sc1
	v_add_u32_e32 v132, 0x2000, v132
	s_waitcnt vmcnt(7)
	v_pk_add_f32 v[36:37], v[36:37], v[136:137]
	v_pk_add_f32 v[38:39], v[38:39], v[138:139]
	s_waitcnt vmcnt(6)
	v_pk_add_f32 v[40:41], v[40:41], v[140:141]
	v_pk_add_f32 v[42:43], v[42:43], v[142:143]
	s_waitcnt vmcnt(5)
	v_pk_add_f32 v[44:45], v[44:45], v[144:145]
	v_pk_add_f32 v[46:47], v[46:47], v[146:147]
	s_waitcnt vmcnt(4)
	v_pk_add_f32 v[48:49], v[48:49], v[148:149]
	v_pk_add_f32 v[50:51], v[50:51], v[150:151]
	s_waitcnt vmcnt(3)
	v_pk_add_f32 v[52:53], v[52:53], v[152:153]
	v_pk_add_f32 v[54:55], v[54:55], v[154:155]
	s_waitcnt vmcnt(2)
	v_pk_add_f32 v[56:57], v[56:57], v[156:157]
	v_pk_add_f32 v[58:59], v[58:59], v[158:159]
	s_waitcnt vmcnt(1)
	v_pk_add_f32 v[60:61], v[60:61], v[160:161]
	v_pk_add_f32 v[62:63], v[62:63], v[162:163]
	s_waitcnt vmcnt(0)
	v_pk_add_f32 v[64:65], v[64:65], v[164:165]
	v_pk_add_f32 v[66:67], v[66:67], v[166:167]
	global_load_dwordx4 v[136:139], v132, s[98:99] sc0 sc1
	v_add_u32_e32 v132, 0x2000, v132
	global_load_dwordx4 v[140:143], v132, s[98:99] sc0 sc1
	v_add_u32_e32 v132, 0x2000, v132
	global_load_dwordx4 v[144:147], v132, s[98:99] sc0 sc1
	v_add_u32_e32 v132, 0x2000, v132
	global_load_dwordx4 v[148:151], v132, s[98:99] sc0 sc1
	v_add_u32_e32 v132, 0x2000, v132
	global_load_dwordx4 v[152:155], v132, s[98:99] sc0 sc1
	v_add_u32_e32 v132, 0x2000, v132
	global_load_dwordx4 v[156:159], v132, s[98:99] sc0 sc1
	v_add_u32_e32 v132, 0x2000, v132
	global_load_dwordx4 v[160:163], v132, s[98:99] sc0 sc1
	v_add_u32_e32 v132, 0x2000, v132
	global_load_dwordx4 v[164:167], v132, s[98:99] sc0 sc1
	v_add_u32_e32 v132, 0x2000, v132
	s_waitcnt vmcnt(7)
	v_pk_add_f32 v[68:69], v[68:69], v[136:137]
	v_pk_add_f32 v[70:71], v[70:71], v[138:139]
	s_waitcnt vmcnt(6)
	v_pk_add_f32 v[72:73], v[72:73], v[140:141]
	v_pk_add_f32 v[74:75], v[74:75], v[142:143]
	s_waitcnt vmcnt(5)
	v_pk_add_f32 v[76:77], v[76:77], v[144:145]
	v_pk_add_f32 v[78:79], v[78:79], v[146:147]
	s_waitcnt vmcnt(4)
	v_pk_add_f32 v[80:81], v[80:81], v[148:149]
	v_pk_add_f32 v[82:83], v[82:83], v[150:151]
	s_waitcnt vmcnt(3)
	v_pk_add_f32 v[84:85], v[84:85], v[152:153]
	v_pk_add_f32 v[86:87], v[86:87], v[154:155]
	s_waitcnt vmcnt(2)
	v_pk_add_f32 v[88:89], v[88:89], v[156:157]
	v_pk_add_f32 v[90:91], v[90:91], v[158:159]
	s_waitcnt vmcnt(1)
	v_pk_add_f32 v[92:93], v[92:93], v[160:161]
	v_pk_add_f32 v[94:95], v[94:95], v[162:163]
	s_waitcnt vmcnt(0)
; #define LAS __attribute__((address_space(3)))
; template <class Epi, int LDA, int LDB, int KK>
; __device__ __forceinline__ void gemm_phase(int wv, LAS unsigned char* lds, const Gemm g, const StaticOrder& S, const Epi& E) {
;     ...
;         E(acc, cur, wr, wc, fr, fq, (const LAS float*)(lds + 131072 + (ui % 3) * 1024));
;         if (!has_next) break;
	v_pk_add_f32 v[96:97], v[96:97], v[164:165]
	v_pk_add_f32 v[98:99], v[98:99], v[166:167]
	global_load_dwordx4 v[136:139], v132, s[98:99] sc0 sc1
	v_add_u32_e32 v132, 0x2000, v132
	global_load_dwordx4 v[140:143], v132, s[98:99] sc0 sc1
	v_add_u32_e32 v132, 0x2000, v132
	global_load_dwordx4 v[144:147], v132, s[98:99] sc0 sc1
	v_add_u32_e32 v132, 0x2000, v132
	global_load_dwordx4 v[148:151], v132, s[98:99] sc0 sc1
	v_add_u32_e32 v132, 0x2000, v132
	global_load_dwordx4 v[152:155], v132, s[98:99] sc0 sc1
	v_add_u32_e32 v132, 0x2000, v132
	global_load_dwordx4 v[156:159], v132, s[98:99] sc0 sc1
	v_add_u32_e32 v132, 0x2000, v132
	global_load_dwordx4 v[160:163], v132, s[98:99] sc0 sc1
	v_add_u32_e32 v132, 0x2000, v132
	global_load_dwordx4 v[164:167], v132, s[98:99] sc0 sc1
	v_add_u32_e32 v132, 0x2000, v132
	s_waitcnt vmcnt(7)
	v_pk_add_f32 v[100:101], v[100:101], v[136:137]
	v_pk_add_f32 v[102:103], v[102:103], v[138:139]
	s_waitcnt vmcnt(6)
	v_pk_add_f32 v[104:105], v[104:105], v[140:141]
	v_pk_add_f32 v[106:107], v[106:107], v[142:143]
	s_waitcnt vmcnt(5)
	v_pk_add_f32 v[108:109], v[108:109], v[144:145]
	v_pk_add_f32 v[110:111], v[110:111], v[146:147]
	s_waitcnt vmcnt(4)
	v_pk_add_f32 v[112:113], v[112:113], v[148:149]
	v_pk_add_f32 v[114:115], v[114:115], v[150:151]
	s_waitcnt vmcnt(3)
	v_pk_add_f32 v[116:117], v[116:117], v[152:153]
	v_pk_add_f32 v[118:119], v[118:119], v[154:155]
	s_waitcnt vmcnt(2)
	v_pk_add_f32 v[120:121], v[120:121], v[156:157]
	v_pk_add_f32 v[122:123], v[122:123], v[158:159]
	s_waitcnt vmcnt(1)
	v_pk_add_f32 v[124:125], v[124:125], v[160:161]
	v_pk_add_f32 v[126:127], v[126:127], v[162:163]
	s_waitcnt vmcnt(0)
	v_pk_add_f32 v[128:129], v[128:129], v[164:165]
	v_pk_add_f32 v[130:131], v[130:131], v[166:167]
	global_load_dwordx4 v[136:139], v132, s[98:99] sc0 sc1
	v_add_u32_e32 v132, 0x2000, v132
	global_load_dwordx4 v[140:143], v132, s[98:99] sc0 sc1
	v_add_u32_e32 v132, 0x2000, v132
	global_load_dwordx4 v[144:147], v132, s[98:99] sc0 sc1
	v_add_u32_e32 v132, 0x2000, v132
	global_load_dwordx4 v[148:151], v132, s[98:99] sc0 sc1
	v_add_u32_e32 v132, 0x2000, v132
	global_load_dwordx4 v[152:155], v132, s[98:99] sc0 sc1
	v_add_u32_e32 v132, 0x2000, v132
	global_load_dwordx4 v[156:159], v132, s[98:99] sc0 sc1
	v_add_u32_e32 v132, 0x2000, v132
	global_load_dwordx4 v[160:163], v132, s[98:99] sc0 sc1
	v_add_u32_e32 v132, 0x2000, v132
	global_load_dwordx4 v[164:167], v132, s[98:99] sc0 sc1
	v_add_u32_e32 v132, 0x2000, v132
	s_waitcnt vmcnt(7)
	v_pk_add_f32 v[4:5], v[4:5], v[136:137]
	v_pk_add_f32 v[6:7], v[6:7], v[138:139]
	s_waitcnt vmcnt(6)
	v_pk_add_f32 v[8:9], v[8:9], v[140:141]
	v_pk_add_f32 v[10:11], v[10:11], v[142:143]
	s_waitcnt vmcnt(5)
	v_pk_add_f32 v[12:13], v[12:13], v[144:145]
	v_pk_add_f32 v[14:15], v[14:15], v[146:147]
	s_waitcnt vmcnt(4)
	v_pk_add_f32 v[16:17], v[16:17], v[148:149]
	v_pk_add_f32 v[18:19], v[18:19], v[150:151]
	s_waitcnt vmcnt(3)
	v_pk_add_f32 v[20:21], v[20:21], v[152:153]
	v_pk_add_f32 v[22:23], v[22:23], v[154:155]
	s_waitcnt vmcnt(2)
	v_pk_add_f32 v[24:25], v[24:25], v[156:157]
	v_pk_add_f32 v[26:27], v[26:27], v[158:159]
	s_waitcnt vmcnt(1)
	v_pk_add_f32 v[28:29], v[28:29], v[160:161]
	v_pk_add_f32 v[30:31], v[30:31], v[162:163]
	s_waitcnt vmcnt(0)
	v_pk_add_f32 v[32:33], v[32:33], v[164:165]
	v_pk_add_f32 v[34:35], v[34:35], v[166:167]
	global_load_dwordx4 v[136:139], v132, s[98:99] sc0 sc1
	v_add_u32_e32 v132, 0x2000, v132
	global_load_dwordx4 v[140:143], v132, s[98:99] sc0 sc1
	v_add_u32_e32 v132, 0x2000, v132
	global_load_dwordx4 v[144:147], v132, s[98:99] sc0 sc1
	v_add_u32_e32 v132, 0x2000, v132
	global_load_dwordx4 v[148:151], v132, s[98:99] sc0 sc1
	v_add_u32_e32 v132, 0x2000, v132
	global_load_dwordx4 v[152:155], v132, s[98:99] sc0 sc1
	v_add_u32_e32 v132, 0x2000, v132
	global_load_dwordx4 v[156:159], v132, s[98:99] sc0 sc1
	v_add_u32_e32 v132, 0x2000, v132
	global_load_dwordx4 v[160:163], v132, s[98:99] sc0 sc1
	v_add_u32_e32 v132, 0x2000, v132
	global_load_dwordx4 v[164:167], v132, s[98:99] sc0 sc1
	v_add_u32_e32 v132, 0x2000, v132
	s_waitcnt vmcnt(7)
	v_pk_add_f32 v[36:37], v[36:37], v[136:137]
	v_pk_add_f32 v[38:39], v[38:39], v[138:139]
	s_waitcnt vmcnt(6)
	v_pk_add_f32 v[40:41], v[40:41], v[140:141]
	v_pk_add_f32 v[42:43], v[42:43], v[142:143]
	s_waitcnt vmcnt(5)
	v_pk_add_f32 v[44:45], v[44:45], v[144:145]
	v_pk_add_f32 v[46:47], v[46:47], v[146:147]
	s_waitcnt vmcnt(4)
	v_pk_add_f32 v[48:49], v[48:49], v[148:149]
	v_pk_add_f32 v[50:51], v[50:51], v[150:151]
	s_waitcnt vmcnt(3)
	v_pk_add_f32 v[52:53], v[52:53], v[152:153]
	v_pk_add_f32 v[54:55], v[54:55], v[154:155]
	s_waitcnt vmcnt(2)
	v_pk_add_f32 v[56:57], v[56:57], v[156:157]
	v_pk_add_f32 v[58:59], v[58:59], v[158:159]
	s_waitcnt vmcnt(1)
	v_pk_add_f32 v[60:61], v[60:61], v[160:161]
	v_pk_add_f32 v[62:63], v[62:63], v[162:163]
	s_waitcnt vmcnt(0)
	v_pk_add_f32 v[64:65], v[64:65], v[164:165]
	v_pk_add_f32 v[66:67], v[66:67], v[166:167]
	global_load_dwordx4 v[136:139], v132, s[98:99] sc0 sc1
	v_add_u32_e32 v132, 0x2000, v132
	global_load_dwordx4 v[140:143], v132, s[98:99] sc0 sc1
	v_add_u32_e32 v132, 0x2000, v132
	global_load_dwordx4 v[144:147], v132, s[98:99] sc0 sc1
	v_add_u32_e32 v132, 0x2000, v132
	global_load_dwordx4 v[148:151], v132, s[98:99] sc0 sc1
	v_add_u32_e32 v132, 0x2000, v132
	global_load_dwordx4 v[152:155], v132, s[98:99] sc0 sc1
	v_add_u32_e32 v132, 0x2000, v132
	global_load_dwordx4 v[156:159], v132, s[98:99] sc0 sc1
	v_add_u32_e32 v132, 0x2000, v132
	global_load_dwordx4 v[160:163], v132, s[98:99] sc0 sc1
	v_add_u32_e32 v132, 0x2000, v132
	global_load_dwordx4 v[164:167], v132, s[98:99] sc0 sc1
	v_add_u32_e32 v132, 0x2000, v132
	s_waitcnt vmcnt(7)
; #define LAS __attribute__((address_space(3)))
; template <class Epi, int LDA, int LDB, int KK>
; __device__ __forceinline__ void gemm_phase(int wv, LAS unsigned char* lds, const Gemm g, const StaticOrder& S, const Epi& E) {
;     ...
;         E(acc, cur, wr, wc, fr, fq, (const LAS float*)(lds + 131072 + (ui % 3) * 1024));
;         if (!has_next) break;
	v_pk_add_f32 v[68:69], v[68:69], v[136:137]
	v_pk_add_f32 v[70:71], v[70:71], v[138:139]
	s_waitcnt vmcnt(6)
	v_pk_add_f32 v[72:73], v[72:73], v[140:141]
	v_pk_add_f32 v[74:75], v[74:75], v[142:143]
	s_waitcnt vmcnt(5)
	v_pk_add_f32 v[76:77], v[76:77], v[144:145]
	v_pk_add_f32 v[78:79], v[78:79], v[146:147]
	s_waitcnt vmcnt(4)
	v_pk_add_f32 v[80:81], v[80:81], v[148:149]
	v_pk_add_f32 v[82:83], v[82:83], v[150:151]
	s_waitcnt vmcnt(3)
	v_pk_add_f32 v[84:85], v[84:85], v[152:153]
	v_pk_add_f32 v[86:87], v[86:87], v[154:155]
	s_waitcnt vmcnt(2)
	v_pk_add_f32 v[88:89], v[88:89], v[156:157]
	v_pk_add_f32 v[90:91], v[90:91], v[158:159]
	s_waitcnt vmcnt(1)
	v_pk_add_f32 v[92:93], v[92:93], v[160:161]
	v_pk_add_f32 v[94:95], v[94:95], v[162:163]
	s_waitcnt vmcnt(0)
	v_pk_add_f32 v[96:97], v[96:97], v[164:165]
	v_pk_add_f32 v[98:99], v[98:99], v[166:167]
	global_load_dwordx4 v[136:139], v132, s[98:99] sc0 sc1
	v_add_u32_e32 v132, 0x2000, v132
	global_load_dwordx4 v[140:143], v132, s[98:99] sc0 sc1
	v_add_u32_e32 v132, 0x2000, v132
	global_load_dwordx4 v[144:147], v132, s[98:99] sc0 sc1
	v_add_u32_e32 v132, 0x2000, v132
	global_load_dwordx4 v[148:151], v132, s[98:99] sc0 sc1
	v_add_u32_e32 v132, 0x2000, v132
	global_load_dwordx4 v[152:155], v132, s[98:99] sc0 sc1
	v_add_u32_e32 v132, 0x2000, v132
	global_load_dwordx4 v[156:159], v132, s[98:99] sc0 sc1
	v_add_u32_e32 v132, 0x2000, v132
	global_load_dwordx4 v[160:163], v132, s[98:99] sc0 sc1
	v_add_u32_e32 v132, 0x2000, v132
	global_load_dwordx4 v[164:167], v132, s[98:99] sc0 sc1
	v_add_u32_e32 v132, 0x2000, v132
	s_waitcnt vmcnt(7)
	v_pk_add_f32 v[100:101], v[100:101], v[136:137]
	v_pk_add_f32 v[102:103], v[102:103], v[138:139]
	s_waitcnt vmcnt(6)
	v_pk_add_f32 v[104:105], v[104:105], v[140:141]
	v_pk_add_f32 v[106:107], v[106:107], v[142:143]
	s_waitcnt vmcnt(5)
	v_pk_add_f32 v[108:109], v[108:109], v[144:145]
	v_pk_add_f32 v[110:111], v[110:111], v[146:147]
	s_waitcnt vmcnt(4)
	v_pk_add_f32 v[112:113], v[112:113], v[148:149]
	v_pk_add_f32 v[114:115], v[114:115], v[150:151]
	s_waitcnt vmcnt(3)
	v_pk_add_f32 v[116:117], v[116:117], v[152:153]
	v_pk_add_f32 v[118:119], v[118:119], v[154:155]
	s_waitcnt vmcnt(2)
	v_pk_add_f32 v[120:121], v[120:121], v[156:157]
	v_pk_add_f32 v[122:123], v[122:123], v[158:159]
	s_waitcnt vmcnt(1)
	v_pk_add_f32 v[124:125], v[124:125], v[160:161]
	v_pk_add_f32 v[126:127], v[126:127], v[162:163]
	s_waitcnt vmcnt(0)
	v_pk_add_f32 v[128:129], v[128:129], v[164:165]
	v_pk_add_f32 v[130:131], v[130:131], v[166:167]
	global_load_dwordx4 v[136:139], v132, s[98:99] sc0 sc1
	v_add_u32_e32 v132, 0x2000, v132
	global_load_dwordx4 v[140:143], v132, s[98:99] sc0 sc1
	v_add_u32_e32 v132, 0x2000, v132
	global_load_dwordx4 v[144:147], v132, s[98:99] sc0 sc1
	v_add_u32_e32 v132, 0x2000, v132
	global_load_dwordx4 v[148:151], v132, s[98:99] sc0 sc1
	v_add_u32_e32 v132, 0x2000, v132
	global_load_dwordx4 v[152:155], v132, s[98:99] sc0 sc1
	v_add_u32_e32 v132, 0x2000, v132
	global_load_dwordx4 v[156:159], v132, s[98:99] sc0 sc1
	v_add_u32_e32 v132, 0x2000, v132
	global_load_dwordx4 v[160:163], v132, s[98:99] sc0 sc1
	v_add_u32_e32 v132, 0x2000, v132
	global_load_dwordx4 v[164:167], v132, s[98:99] sc0 sc1
	v_add_u32_e32 v132, 0x2000, v132
	s_waitcnt vmcnt(7)
	v_pk_add_f32 v[4:5], v[4:5], v[136:137]
	v_pk_add_f32 v[6:7], v[6:7], v[138:139]
	s_waitcnt vmcnt(6)
	v_pk_add_f32 v[8:9], v[8:9], v[140:141]
	v_pk_add_f32 v[10:11], v[10:11], v[142:143]
	s_waitcnt vmcnt(5)
	v_pk_add_f32 v[12:13], v[12:13], v[144:145]
	v_pk_add_f32 v[14:15], v[14:15], v[146:147]
	s_waitcnt vmcnt(4)
	v_pk_add_f32 v[16:17], v[16:17], v[148:149]
	v_pk_add_f32 v[18:19], v[18:19], v[150:151]
	s_waitcnt vmcnt(3)
	v_pk_add_f32 v[20:21], v[20:21], v[152:153]
	v_pk_add_f32 v[22:23], v[22:23], v[154:155]
	s_waitcnt vmcnt(2)
	v_pk_add_f32 v[24:25], v[24:25], v[156:157]
	v_pk_add_f32 v[26:27], v[26:27], v[158:159]
	s_waitcnt vmcnt(1)
	v_pk_add_f32 v[28:29], v[28:29], v[160:161]
	v_pk_add_f32 v[30:31], v[30:31], v[162:163]
	s_waitcnt vmcnt(0)
	v_pk_add_f32 v[32:33], v[32:33], v[164:165]
	v_pk_add_f32 v[34:35], v[34:35], v[166:167]
	global_load_dwordx4 v[136:139], v132, s[98:99] sc0 sc1
	v_add_u32_e32 v132, 0x2000, v132
	global_load_dwordx4 v[140:143], v132, s[98:99] sc0 sc1
	v_add_u32_e32 v132, 0x2000, v132
	global_load_dwordx4 v[144:147], v132, s[98:99] sc0 sc1
	v_add_u32_e32 v132, 0x2000, v132
	global_load_dwordx4 v[148:151], v132, s[98:99] sc0 sc1
	v_add_u32_e32 v132, 0x2000, v132
	global_load_dwordx4 v[152:155], v132, s[98:99] sc0 sc1
	v_add_u32_e32 v132, 0x2000, v132
	global_load_dwordx4 v[156:159], v132, s[98:99] sc0 sc1
	v_add_u32_e32 v132, 0x2000, v132
	global_load_dwordx4 v[160:163], v132, s[98:99] sc0 sc1
	v_add_u32_e32 v132, 0x2000, v132
	global_load_dwordx4 v[164:167], v132, s[98:99] sc0 sc1
	v_add_u32_e32 v132, 0x2000, v132
	s_waitcnt vmcnt(7)
	v_pk_add_f32 v[36:37], v[36:37], v[136:137]
	v_pk_add_f32 v[38:39], v[38:39], v[138:139]
	s_waitcnt vmcnt(6)
	v_pk_add_f32 v[40:41], v[40:41], v[140:141]
	v_pk_add_f32 v[42:43], v[42:43], v[142:143]
	s_waitcnt vmcnt(5)
	v_pk_add_f32 v[44:45], v[44:45], v[144:145]
	v_pk_add_f32 v[46:47], v[46:47], v[146:147]
	s_waitcnt vmcnt(4)
	v_pk_add_f32 v[48:49], v[48:49], v[148:149]
	v_pk_add_f32 v[50:51], v[50:51], v[150:151]
	s_waitcnt vmcnt(3)
	v_pk_add_f32 v[52:53], v[52:53], v[152:153]
	v_pk_add_f32 v[54:55], v[54:55], v[154:155]
	s_waitcnt vmcnt(2)
	v_pk_add_f32 v[56:57], v[56:57], v[156:157]
	v_pk_add_f32 v[58:59], v[58:59], v[158:159]
	s_waitcnt vmcnt(1)
	v_pk_add_f32 v[60:61], v[60:61], v[160:161]
	v_pk_add_f32 v[62:63], v[62:63], v[162:163]
	s_waitcnt vmcnt(0)
; #define LAS __attribute__((address_space(3)))
; template <class Epi, int LDA, int LDB, int KK>
; __device__ __forceinline__ void gemm_phase(int wv, LAS unsigned char* lds, const Gemm g, const StaticOrder& S, const Epi& E) {
;     ...
;         E(acc, cur, wr, wc, fr, fq, (const LAS float*)(lds + 131072 + (ui % 3) * 1024));
;         if (!has_next) break;
	v_pk_add_f32 v[64:65], v[64:65], v[164:165]
	v_pk_add_f32 v[66:67], v[66:67], v[166:167]
	global_load_dwordx4 v[136:139], v132, s[98:99] sc0 sc1
	v_add_u32_e32 v132, 0x2000, v132
	global_load_dwordx4 v[140:143], v132, s[98:99] sc0 sc1
	v_add_u32_e32 v132, 0x2000, v132
	global_load_dwordx4 v[144:147], v132, s[98:99] sc0 sc1
	v_add_u32_e32 v132, 0x2000, v132
	global_load_dwordx4 v[148:151], v132, s[98:99] sc0 sc1
	v_add_u32_e32 v132, 0x2000, v132
	global_load_dwordx4 v[152:155], v132, s[98:99] sc0 sc1
	v_add_u32_e32 v132, 0x2000, v132
	global_load_dwordx4 v[156:159], v132, s[98:99] sc0 sc1
	v_add_u32_e32 v132, 0x2000, v132
	global_load_dwordx4 v[160:163], v132, s[98:99] sc0 sc1
	v_add_u32_e32 v132, 0x2000, v132
	global_load_dwordx4 v[164:167], v132, s[98:99] sc0 sc1
	v_add_u32_e32 v132, 0x2000, v132
	s_waitcnt vmcnt(7)
	v_pk_add_f32 v[68:69], v[68:69], v[136:137]
	v_pk_add_f32 v[70:71], v[70:71], v[138:139]
	s_waitcnt vmcnt(6)
	v_pk_add_f32 v[72:73], v[72:73], v[140:141]
	v_pk_add_f32 v[74:75], v[74:75], v[142:143]
	s_waitcnt vmcnt(5)
	v_pk_add_f32 v[76:77], v[76:77], v[144:145]
	v_pk_add_f32 v[78:79], v[78:79], v[146:147]
	s_waitcnt vmcnt(4)
	v_pk_add_f32 v[80:81], v[80:81], v[148:149]
	v_pk_add_f32 v[82:83], v[82:83], v[150:151]
	s_waitcnt vmcnt(3)
	v_pk_add_f32 v[84:85], v[84:85], v[152:153]
	v_pk_add_f32 v[86:87], v[86:87], v[154:155]
	s_waitcnt vmcnt(2)
	v_pk_add_f32 v[88:89], v[88:89], v[156:157]
	v_pk_add_f32 v[90:91], v[90:91], v[158:159]
	s_waitcnt vmcnt(1)
	v_pk_add_f32 v[92:93], v[92:93], v[160:161]
	v_pk_add_f32 v[94:95], v[94:95], v[162:163]
	s_waitcnt vmcnt(0)
	v_pk_add_f32 v[96:97], v[96:97], v[164:165]
	v_pk_add_f32 v[98:99], v[98:99], v[166:167]
	global_load_dwordx4 v[136:139], v132, s[98:99] sc0 sc1
	v_add_u32_e32 v132, 0x2000, v132
	global_load_dwordx4 v[140:143], v132, s[98:99] sc0 sc1
	v_add_u32_e32 v132, 0x2000, v132
	global_load_dwordx4 v[144:147], v132, s[98:99] sc0 sc1
	v_add_u32_e32 v132, 0x2000, v132
	global_load_dwordx4 v[148:151], v132, s[98:99] sc0 sc1
	v_add_u32_e32 v132, 0x2000, v132
	global_load_dwordx4 v[152:155], v132, s[98:99] sc0 sc1
	v_add_u32_e32 v132, 0x2000, v132
	global_load_dwordx4 v[156:159], v132, s[98:99] sc0 sc1
	v_add_u32_e32 v132, 0x2000, v132
	global_load_dwordx4 v[160:163], v132, s[98:99] sc0 sc1
	v_add_u32_e32 v132, 0x2000, v132
	global_load_dwordx4 v[164:167], v132, s[98:99] sc0 sc1
	s_waitcnt vmcnt(7)
	v_pk_add_f32 v[100:101], v[100:101], v[136:137]
	v_pk_add_f32 v[102:103], v[102:103], v[138:139]
	s_waitcnt vmcnt(6)
	v_pk_add_f32 v[104:105], v[104:105], v[140:141]
	v_pk_add_f32 v[106:107], v[106:107], v[142:143]
	s_waitcnt vmcnt(5)
	v_pk_add_f32 v[108:109], v[108:109], v[144:145]
	v_pk_add_f32 v[110:111], v[110:111], v[146:147]
	s_waitcnt vmcnt(4)
	v_pk_add_f32 v[112:113], v[112:113], v[148:149]
	v_pk_add_f32 v[114:115], v[114:115], v[150:151]
	s_waitcnt vmcnt(3)
	v_pk_add_f32 v[116:117], v[116:117], v[152:153]
	v_pk_add_f32 v[118:119], v[118:119], v[154:155]
	s_waitcnt vmcnt(2)
	v_pk_add_f32 v[120:121], v[120:121], v[156:157]
	v_pk_add_f32 v[122:123], v[122:123], v[158:159]
	s_waitcnt vmcnt(1)
	v_pk_add_f32 v[124:125], v[124:125], v[160:161]
	v_pk_add_f32 v[126:127], v[126:127], v[162:163]
	s_waitcnt vmcnt(0)
	v_pk_add_f32 v[128:129], v[128:129], v[164:165]
	v_pk_add_f32 v[130:131], v[130:131], v[166:167]
; __device__ __forceinline__ float shx(float v, int mask, int lane) { return __int_as_float(__builtin_amdgcn_ds_bpermute((lane ^ mask) << 2, __float_as_int(v))); }
; __device__ __forceinline__ u32x4 pack8(const f32x4& a, const f32x4& b) { u32x4 w; w.x = pack2(a[0], a[1]); w.y = pack2(a[2], a[3]); w.z = pack2(b[0], b[1]); w.w = pack2(b[2], b[3]); return w; }
;     __device__ __forceinline__ void operator()(AccT& acc, const pg8::Unit& u, int wr, int wc, int fr, int fq, const LAS float* rs) const {
;         int row0 = u.pm * 256 + wr * 64 + fr; asm volatile("" : "+v"(row0)); const int cb = u.pn * 256 + wc * 32 + 8 * fq, lane = fr + 16 * fq;
; #pragma unroll
;         for (int ai = 0; ai < 2; ++ai) {
;             f32x4 hv[4][2][2];
; #pragma unroll
;             for (int m = 0; m < 4; ++m)
; #pragma unroll
;                 for (int bj = 0; bj < 2; ++bj) { const float* hp = h + (size_t)(row0 + ai * 128 + m * 16) * D + cb + bj * 128; hv[m][bj][0] = *(const f32x4*)hp; hv[m][bj][1] = *(const f32x4*)(hp + 4); }
; #pragma unroll
;             for (int m = 0; m < 4; ++m) {
;                 const int row = row0 + ai * 128 + m * 16; float ss = 0.f;
; #pragma unroll
;                 for (int bj = 0; bj < 2; ++bj) {
;                     const int col = cb + bj * 128; float* hp = h + (size_t)row * D + col;
;                     const f32x4 o0 = hv[m][bj][0] + acc[ai][bj][m][0], o1 = hv[m][bj][1] + acc[ai][bj][m][1];
;                     *(f32x4*)hp = o0; *(f32x4*)(hp + 4) = o1;
;                     *(u32x4*)(hb + (size_t)row * D + col) = pack8(o0, o1);
;                     ss += o0[0] * o0[0] + o0[1] * o0[1] + o0[2] * o0[2] + o0[3] * o0[3] + o1[0] * o1[0] + o1[1] * o1[1] + o1[2] * o1[2] + o1[3] * o1[3];
;                 }
;                 ss += shx(ss, 16, lane); ss += shx(ss, 32, lane);
;                 if (fq == 0) atomicAdd(rsqn + row, ss);
.Ldn_epi:
	v_lshl_or_b32 v202, s45, 8, v233
	v_lshl_add_u32 v206, s46, 8, v197
	v_ashrrev_i32_e32 v203, 31, v202
	v_lshlrev_b64 v[244:245], 2, v[202:203]
	v_ashrrev_i32_e32 v207, 31, v206
	v_lshl_add_u64 v[204:205], s[14:15], 0, v[244:245]
	v_lshlrev_b64 v[246:247], 13, v[206:207]
	v_lshl_add_u64 v[132:133], v[204:205], 0, v[246:247]
	global_load_dwordx4 v[236:239], v[132:133], off offset:16
	global_load_dwordx4 v[240:243], v[132:133], off
	global_load_dwordx4 v[180:183], v[132:133], off offset:528
	global_load_dwordx4 v[184:187], v[132:133], off offset:512
	v_add_u32_e32 v214, 16, v206
	v_ashrrev_i32_e32 v215, 31, v214
	v_add_u32_e32 v210, 32, v206
	v_add_u32_e32 v208, 48, v206
	v_lshlrev_b64 v[218:219], 13, v[214:215]
	v_ashrrev_i32_e32 v211, 31, v210
	v_ashrrev_i32_e32 v209, 31, v208
	v_lshl_add_u64 v[132:133], v[204:205], 0, v[218:219]
	v_lshlrev_b64 v[216:217], 13, v[210:211]
	v_lshlrev_b64 v[212:213], 13, v[208:209]
	global_load_dwordx4 v[172:175], v[132:133], off offset:16
	global_load_dwordx4 v[176:179], v[132:133], off
	global_load_dwordx4 v[164:167], v[132:133], off offset:528
	global_load_dwordx4 v[168:171], v[132:133], off offset:512
	v_lshl_add_u64 v[132:133], v[204:205], 0, v[216:217]
	v_lshl_add_u64 v[136:137], v[204:205], 0, v[212:213]
	global_load_dwordx4 v[156:159], v[132:133], off offset:16
	global_load_dwordx4 v[160:163], v[132:133], off
	global_load_dwordx4 v[140:143], v[132:133], off offset:528
	global_load_dwordx4 v[148:151], v[132:133], off offset:512
	global_load_dwordx4 v[144:147], v[136:137], off offset:16
	global_load_dwordx4 v[152:155], v[136:137], off
	s_nop 0
	global_load_dwordx4 v[132:135], v[136:137], off offset:528
	s_nop 0
	global_load_dwordx4 v[136:139], v[136:137], off offset:512
	v_lshl_add_u64 v[246:247], s[14:15], 0, v[246:247]
	v_lshl_add_u64 v[244:245], v[246:247], 0, v[244:245]
	s_waitcnt vmcnt(0)
	v_pk_add_f32 v[126:127], v[126:127], v[238:239]
	v_pk_add_f32 v[130:131], v[130:131], v[242:243]
	v_pk_add_f32 v[128:129], v[128:129], v[240:241]
	v_pk_add_f32 v[124:125], v[124:125], v[236:237]
	global_store_dwordx4 v[244:245], v[128:131], off
	global_store_dwordx4 v[244:245], v[124:127], off offset:16
	v_cvt_pk_bf16_f32 v236, v128, v129
	v_lshlrev_b64 v[240:241], 12, v[206:207]
	v_mul_f32_e32 v129, v129, v129
	v_fmac_f32_e32 v129, v128, v128
	v_lshl_add_u64 v[240:241], s[12:13], 0, v[240:241]
	v_fmac_f32_e32 v129, v130, v130
	v_lshl_add_u64 v[240:241], v[202:203], 1, v[240:241]
	v_fmac_f32_e32 v129, v131, v131
	v_pk_add_f32 v[122:123], v[122:123], v[186:187]
	v_pk_add_f32 v[120:121], v[120:121], v[184:185]
	v_cvt_pk_bf16_f32 v237, v130, v131
	v_cvt_pk_bf16_f32 v238, v124, v125
	v_cvt_pk_bf16_f32 v239, v126, v127
	global_store_dwordx4 v[240:241], v[236:239], off
	v_fmac_f32_e32 v129, v124, v124
	v_pk_add_f32 v[118:119], v[118:119], v[182:183]
	v_pk_add_f32 v[116:117], v[116:117], v[180:181]
	global_store_dwordx4 v[244:245], v[120:123], off offset:512
	global_store_dwordx4 v[244:245], v[116:119], off offset:528
	v_cvt_pk_bf16_f32 v124, v120, v121
	v_fmac_f32_e32 v129, v125, v125
	v_mul_f32_e32 v121, v121, v121
	v_fmac_f32_e32 v121, v120, v120
	v_fmac_f32_e32 v121, v122, v122
	v_fmac_f32_e32 v121, v123, v123
	v_fmac_f32_e32 v121, v116, v116
	v_fmac_f32_e32 v121, v117, v117
	v_fmac_f32_e32 v129, v126, v126
	v_fmac_f32_e32 v121, v118, v118
	v_fmac_f32_e32 v129, v127, v127
	v_fmac_f32_e32 v121, v119, v119
	v_cvt_pk_bf16_f32 v126, v116, v117
	v_add_f32_e32 v116, v129, v121
	ds_bpermute_b32 v117, v231, v116
	v_cvt_pk_bf16_f32 v125, v122, v123
	v_cvt_pk_bf16_f32 v127, v118, v119
	global_store_dwordx4 v[240:241], v[124:127], off offset:256
	s_waitcnt lgkmcnt(0)
	v_add_f32_e32 v116, v116, v117
	ds_bpermute_b32 v117, v232, v116
	s_and_saveexec_b64 s[18:19], s[4:5]
	s_cbranch_execz .LBB0_928
	s_waitcnt lgkmcnt(0)
	v_add_f32_e32 v118, v116, v117
	v_lshl_add_u64 v[116:117], v[206:207], 2, s[16:17]
	global_atomic_add_f32 v[116:117], v118, off

; #define LAS __attribute__((address_space(3)))
; __device__ __forceinline__ PP get_params() { unsigned long long kp = (unsigned long long)__builtin_amdgcn_kernarg_segment_ptr(); asm volatile("" : "+s"(kp)); return (PP)kp; }
; __device__ __forceinline__ int opaque_tid(int wv) { asm volatile("" : "+s"(wv)); unsigned z = 0u; asm volatile("" : "+v"(z)); const int l = __builtin_amdgcn_mbcnt_hi(~0u, __builtin_amdgcn_mbcnt_lo(~0u, z)); return (wv << 6) | l; }
; __device__ __forceinline__ int opaque_bid() { int t = blockIdx.x; asm volatile("" : "+s"(t)); return t; }
; __device__ __forceinline__ void convert_weight(int wv, const float* __restrict__ src, int ldsrc, int Ksrc, bf16_t* dst, int ldd, int koff, int ntn, const float* kscale, int mode, LAS float* tile, int pidx, int pcnt) {
;     const int tid = opaque_tid(wv); const int ntk = Ksrc / 128; const int total = ntn * ntk; const int G = pcnt;
;     const int kk0 = tid >> 4, n4 = (tid & 15) * 4;
;     f32x4 v[4]; float ks[4];
;     auto prefetch = [&](int t) {
;         const int tn = t % ntn, tk = t / ntn; const int n0 = tn * 64, k0 = tk * 128;
;         int scol = n0, nvalid = 64;
;         if (mode == 1) { if (n0 < 5632) scol = n0; else if (n0 < 13312) scol = n0 + 8; else if (n0 == 13312) { scol = 5632; nvalid = 8; } else { scol = 0; nvalid = 0; } }
; #pragma unroll
;         for (int i = 0; i < 4; ++i) { const int kk = kk0 + i * 32; v[i] = (f32x4){0.f, 0.f, 0.f, 0.f};
;             if (n4 < nvalid) v[i] = *(const f32x4*)(src + (size_t)(k0 + kk) * ldsrc + scol + n4);
;             ks[i] = kscale ? kscale[k0 + kk] : 1.0f; }
; __device__ __forceinline__ void fill_convert(int wv, LAS unsigned char* lds, int nunits, int L, int mask) {
;     const int G = (int)gridDim.x, extra = nunits % G, bid = opaque_bid();
;     if (extra != 0 && bid >= extra) convert_layer(wv, get_params(), L, mask, (LAS float*)lds, bid - extra, G - extra);
.LBB0_945:
	v_readlane_b32 s4, v254, 30
	v_readlane_b32 s5, v254, 31
	s_and_b64 vcc, exec, s[4:5]
	s_cbranch_vccnz .LBB0_970
	s_mov_b32 s4, s81
	s_movk_i32 s5, 64
	s_cmp_lt_i32 s4, s5
	s_cselect_b64 s[6:7], -1, 0
	s_or_b64 s[6:7], s[82:83], s[6:7]
	s_and_b64 vcc, exec, s[6:7]
	s_cbranch_vccnz .LBB0_970
	s_movk_i32 s5, 64
	s_sub_i32 s16, s4, s5
	s_mov_b64 s[10:11], s[0:1]
	s_mov_b32 s4, s95
	v_mov_b32_e32 v0, v3
	s_cmpk_gt_i32 s16, 0xaff
	s_cbranch_scc1 .LBB0_969
	s_load_dwordx4 s[20:23], s[10:11], 0x68
	v_mbcnt_lo_u32_b32 v0, -1, v0
	v_mbcnt_hi_u32_b32 v28, -1, v0
	v_lshl_or_b32 v29, s4, 6, v28
	s_sext_i32_i16 s4, s16
	s_waitcnt lgkmcnt(0)
	s_add_u32 s6, s22, 0x5800000
	s_addc_u32 s7, s23, 0
	s_add_u32 s8, s20, 0x2000
	s_mulk_i32 s4, 0xba3
	s_addc_u32 s9, s21, 0
	s_lshr_b32 s5, s4, 31
	s_ashr_i32 s4, s4, 19
	s_add_i32 s4, s4, s5
	s_mul_i32 s5, s4, 0xb0
	s_sub_i32 s5, s16, s5
	v_ashrrev_i32_e32 v1, 4, v29
	s_sext_i32_i16 s5, s5
	s_lshl_b32 s17, s4, 7
	v_lshlrev_b32_e32 v0, 2, v28
	s_lshl_b32 s12, s5, 6
	v_add_u32_e32 v8, s17, v1
	v_mov_b64_e32 v[4:5], s[6:7]
	s_mov_b32 s4, 0xb000
	v_and_b32_e32 v0, 60, v0
	s_ashr_i32 s13, s12, 31
	v_mad_i64_i32 v[4:5], s[4:5], v8, s4, v[4:5]
	v_lshl_add_u64 v[4:5], s[12:13], 2, v[4:5]
	v_lshlrev_b32_e32 v2, 2, v0
	v_lshl_add_u64 v[4:5], v[4:5], 0, v[2:3]
	global_load_dwordx4 v[4:7], v[4:5], off
	s_cmp_lg_u64 s[20:21], 0
	v_mov_b32_e32 v0, 1.0
	s_cselect_b64 s[14:15], -1, 0
	s_cmp_eq_u64 s[20:21], 0
	v_mov_b32_e32 v20, 1.0
	s_cbranch_scc1 .LBB0_950
	v_ashrrev_i32_e32 v9, 31, v8
	v_lshl_add_u64 v[8:9], v[8:9], 2, s[8:9]
	global_load_dword v20, v[8:9], off

; #define LAS __attribute__((address_space(3)))
; __device__ __forceinline__ void convert_weight(int wv, const float* __restrict__ src, int ldsrc, int Ksrc, bf16_t* dst, int ldd, int koff, int ntn, const float* kscale, int mode, LAS float* tile, int pidx, int pcnt) {
;     ...
;     int t = pidx; int buf = 0;
;     if (t < total) prefetch(t);
;     for (; t < total; t += G) {
;         LAS float* tl = tile + buf * (128 * 65);
.LBB0_956:
	s_load_dwordx2 s[10:11], s[10:11], 0x98
	v_lshlrev_b32_e32 v22, 4, v28
	v_and_b32_e32 v22, 0x70, v22
	v_ashrrev_i32_e32 v30, 3, v29
	v_mul_u32_u24_e32 v31, 0x104, v22
	s_waitcnt lgkmcnt(0)
	s_add_u32 s10, s10, 0x5200000
	s_addc_u32 s11, s11, 0
	v_mul_lo_u32 v32, v1, s87
	s_lshl_b32 s19, s16, 6
	s_sub_u32 s98, s48, 64
	s_lshl_b32 s17, s98, 6
	s_mov_b32 s18, 0
	v_lshlrev_b32_e32 v22, 1, v22
	s_branch .LBB0_958

; #define LAS __attribute__((address_space(3)))
; __device__ __forceinline__ void lds_barrier() { asm volatile("s_waitcnt lgkmcnt(0)" ::: "memory"); __builtin_amdgcn_s_barrier(); asm volatile("" ::: "memory"); }
; __device__ __forceinline__ void convert_weight(int wv, const float* __restrict__ src, int ldsrc, int Ksrc, bf16_t* dst, int ldd, int koff, int ntn, const float* kscale, int mode, LAS float* tile, int pidx, int pcnt) {
;     ...
;         LAS float* tl = tile + buf * (128 * 65);
; #pragma unroll
;         for (int i = 0; i < 4; ++i) { const int kk = kk0 + i * 32;
;             tl[kk * 65 + n4 + 0] = v[i][0] * ks[i]; tl[kk * 65 + n4 + 1] = v[i][1] * ks[i]; tl[kk * 65 + n4 + 2] = v[i][2] * ks[i]; tl[kk * 65 + n4 + 3] = v[i][3] * ks[i]; }
;         lds_barrier();
;         const int tn = t % ntn, tk = t / ntn; const int n0 = tn * 64, k0 = tk * 128;
;         if (t + G < total) prefetch(t + G);
.LBB0_958:
	s_mul_i32 s12, s18, 0x8200
	s_add_i32 s22, s12, 0
	v_add3_u32 v23, s22, v2, v32
	s_waitcnt vmcnt(3)
	v_pk_mul_f32 v[28:29], v[4:5], v[20:21] op_sel_hi:[1,0]
	ds_write2_b32 v23, v28, v29 offset1:1
	v_pk_mul_f32 v[28:29], v[6:7], v[20:21] op_sel_hi:[1,0]
	ds_write2_b32 v23, v28, v29 offset0:2 offset1:3
	s_waitcnt vmcnt(2)
	v_pk_mul_f32 v[28:29], v[8:9], v[0:1] op_sel_hi:[1,0]
	v_add_u32_e32 v33, 0x2080, v23
	ds_write2_b32 v33, v28, v29 offset1:1
	v_pk_mul_f32 v[28:29], v[10:11], v[0:1] op_sel_hi:[1,0]
	v_add_u32_e32 v33, 0x2088, v23
	ds_write2_b32 v33, v28, v29 offset1:1
	s_waitcnt vmcnt(1)
	v_pk_mul_f32 v[28:29], v[12:13], v[26:27] op_sel_hi:[1,0]
	v_add_u32_e32 v33, 0x4100, v23
	ds_write2_b32 v33, v28, v29 offset1:1
	v_pk_mul_f32 v[28:29], v[14:15], v[26:27] op_sel_hi:[1,0]
	v_add_u32_e32 v33, 0x4108, v23
	ds_write2_b32 v33, v28, v29 offset1:1
	s_waitcnt vmcnt(0)
	v_pk_mul_f32 v[28:29], v[16:17], v[24:25] op_sel_hi:[1,0]
	v_add_u32_e32 v33, 0x6180, v23
	ds_write2_b32 v33, v28, v29 offset1:1
	v_pk_mul_f32 v[28:29], v[18:19], v[24:25] op_sel_hi:[1,0]
	v_add_u32_e32 v23, 0x6188, v23
	ds_write2_b32 v23, v28, v29 offset1:1
	s_waitcnt lgkmcnt(0)
	s_barrier
	s_sub_u32 s98, s48, 64
	s_add_i32 s20, s16, s98
	s_cmpk_gt_i32 s20, 0xaff
	s_cselect_b64 s[12:13], -1, 0
	s_cmpk_lt_i32 s20, 0xb00
	s_mov_b64 s[14:15], -1
	s_cbranch_scc1 .LBB0_960
	s_add_i32 s21, s19, s17
	s_mov_b64 s[14:15], 0
